# v81 + GU epilogue: leading half's alignment barrier deferred ~110 instructions into its SwiGLU epilogue so its first VALU stretch overlaps the trailing half's last MMA segment
# baseline (speedup 1.0000x reference)
; #define PG8_STAGE(bufoff, gbase, voff) do { _Pragma("unroll") for (int _i = 0; _i < 2; ++_i) \
;         __builtin_amdgcn_global_load_lds((const unsigned*)((const char*)(gbase) + (voff)[_i]), (PG8_LAS unsigned*)(lds + (bufoff) + ldsw + _i * 8192), 16, 0, 0); } while (0)
; #define PG8_LDA(dst, b, h) do { _Pragma("unroll") for (int m = 0; m < 4; ++m) _Pragma("unroll") for (int k = 0; k < 2; ++k) dst[m][k] = *(const PG8_LAS bf16x8*)(lds + PG8_SA(b, h) + aoff + m * 2048 + k * 1024); } while (0)
; #define PG8_LDB(dst, b, h) do { _Pragma("unroll") for (int n = 0; n < 2; ++n) _Pragma("unroll") for (int k = 0; k < 2; ++k) dst[n][k] = *(const PG8_LAS bf16x8*)(lds + PG8_SB(b, h) + boff + n * 2048 + k * 1024); } while (0)
; #define PG8_MMA(ai, bj, At, Bt) do { __builtin_amdgcn_s_setprio(1); _Pragma("unroll") for (int m = 0; m < 4; ++m) _Pragma("unroll") for (int n = 0; n < 2; ++n) _Pragma("unroll") for (int k = 0; k < 2; ++k) \
;         acc[ai][bj][m][n] = __builtin_amdgcn_mfma_f32_16x16x32_bf16(Bt[n][k], At[m][k], acc[ai][bj][m][n], 0, 0, 0); __builtin_amdgcn_s_setprio(0); } while (0)
; #define PG8_WAIT_L(n) asm volatile("s_waitcnt lgkmcnt(" #n ")" ::: "memory")
; #define PG8_WAIT_VK do { if constexpr (HALFM) PG8_WAIT_V(6); else PG8_WAIT_V(8); } while (0)
; #define PG8_BAR __builtin_amdgcn_s_barrier()
; #define PG8_SCHED __builtin_amdgcn_sched_barrier(0)
; template <class Epi, class Sched, bool ALIGN_EPI = false, bool SP2 = false, bool HALFM = false, bool AMAP = false>
; __device__ __forceinline__ void gemm_phase(PG8_LAS unsigned char* lds, const Gemm g, const Sched& S, const Epi& E, int tid_in) {
;     ...
;             PG8_LDB(B0, 0, 0); PG8_LDB(B1, 0, 1); PG8_SCHED; PG8_LDA(At, 0, 0); if constexpr (!HALFM) PG8_STAGE(PG8_SA(1, 1), a1 + hstepA, voffA);
;             PG8_WAIT_VK; PG8_WAIT_L(0); PG8_BAR; PG8_MMA(0, 0, At, B0); PG8_MMA(0, 1, At, B1); PG8_BAR; PG8_SCHED;
;             if constexpr (!HALFM) { PG8_LDA(At, 0, 1); } PG8_STAGE(PG8_SB(0, 0), b2, voffB); PG8_STAGE(PG8_SB(0, 1), b2 + hstepB, voffB); PG8_STAGE(PG8_SA(0, 0), a2, voffA);
;             PG8_WAIT_VK; PG8_WAIT_L(0); PG8_BAR; if constexpr (!HALFM) { PG8_MMA(1, 0, At, B0); PG8_MMA(1, 1, At, B1); } PG8_BAR; PG8_SCHED;
.LBB0_163:
	s_add_u32 s28, s6, 0xfff80080
	s_addc_u32 s29, s7, -1
	s_add_i32 s76, 0, 0x10000
	s_cmp_eq_u32 s63, 28
	s_cselect_b32 s31, s23, s29
	s_cselect_b32 s30, s59, s28
	s_cselect_b32 s29, s43, s62
	s_cselect_b32 s28, s60, s61
	s_add_i32 s77, 0, 0x14000
	v_add_u32_e32 v140, s76, v205
	v_add_u32_e32 v156, s77, v205
	ds_read_b128 v[0:3], v140
	ds_read_b128 v[4:7], v140 offset:1024
	ds_read_b128 v[136:139], v140 offset:2048
	ds_read_b128 v[140:143], v140 offset:3072
	ds_read_b128 v[144:147], v156
	ds_read_b128 v[148:151], v156 offset:1024
	ds_read_b128 v[152:155], v156 offset:2048
	ds_read_b128 v[156:159], v156 offset:3072
	v_lshl_add_u64 v[218:219], s[6:7], 0, v[190:191]
	s_add_i32 m0, s11, 0xc000
	ds_read_b128 v[160:163], v208
	ds_read_b128 v[164:167], v208 offset:1024
	ds_read_b128 v[168:171], v208 offset:2048
	ds_read_b128 v[192:195], v208 offset:3072
	ds_read_b128 v[196:199], v208 offset:4096
	ds_read_b128 v[200:203], v208 offset:5120
	ds_read_b128 v[210:213], v208 offset:6144
	ds_read_b128 v[214:217], v208 offset:7168
	global_load_lds_dwordx4 v[218:219], off
	v_lshl_add_u64 v[218:219], s[6:7], 0, v[188:189]
	s_add_i32 m0, s11, 0xe000
	s_nop 0
	global_load_lds_dwordx4 v[218:219], off
	s_waitcnt vmcnt(8)
	s_waitcnt lgkmcnt(0)
	s_barrier
	s_setprio 1
	v_mfma_f32_16x16x32_bf16 v[132:135], v[0:3], v[160:163], v[132:135]
	v_mfma_f32_16x16x32_bf16 v[128:131], v[136:139], v[160:163], v[128:131]
	v_mfma_f32_16x16x32_bf16 v[116:119], v[0:3], v[168:171], v[116:119]
	v_mfma_f32_16x16x32_bf16 v[112:115], v[136:139], v[168:171], v[112:115]
	v_mfma_f32_16x16x32_bf16 v[100:103], v[0:3], v[196:199], v[100:103]
	v_mfma_f32_16x16x32_bf16 v[96:99], v[136:139], v[196:199], v[96:99]
	v_mfma_f32_16x16x32_bf16 v[84:87], v[0:3], v[210:213], v[84:87]
	v_mfma_f32_16x16x32_bf16 v[80:83], v[136:139], v[210:213], v[80:83]
	v_mfma_f32_16x16x32_bf16 v[132:135], v[4:7], v[164:167], v[132:135]
	v_mfma_f32_16x16x32_bf16 v[128:131], v[140:143], v[164:167], v[128:131]
	v_mfma_f32_16x16x32_bf16 v[116:119], v[4:7], v[192:195], v[116:119]
	v_mfma_f32_16x16x32_bf16 v[112:115], v[140:143], v[192:195], v[112:115]
	v_mfma_f32_16x16x32_bf16 v[100:103], v[4:7], v[200:203], v[100:103]
	v_mfma_f32_16x16x32_bf16 v[96:99], v[140:143], v[200:203], v[96:99]
	v_mfma_f32_16x16x32_bf16 v[84:87], v[4:7], v[214:217], v[84:87]
	v_mfma_f32_16x16x32_bf16 v[80:83], v[140:143], v[214:217], v[80:83]
	s_setprio 0
	s_setprio 1
	v_mfma_f32_16x16x32_bf16 v[124:127], v[144:147], v[160:163], v[124:127]
	v_mfma_f32_16x16x32_bf16 v[120:123], v[152:155], v[160:163], v[120:123]
	v_mfma_f32_16x16x32_bf16 v[108:111], v[144:147], v[168:171], v[108:111]
	v_mfma_f32_16x16x32_bf16 v[104:107], v[152:155], v[168:171], v[104:107]
	v_mfma_f32_16x16x32_bf16 v[92:95], v[144:147], v[196:199], v[92:95]
	v_mfma_f32_16x16x32_bf16 v[88:91], v[152:155], v[196:199], v[88:91]
	v_mfma_f32_16x16x32_bf16 v[76:79], v[144:147], v[210:213], v[76:79]
	v_mfma_f32_16x16x32_bf16 v[72:75], v[152:155], v[210:213], v[72:75]
	v_mfma_f32_16x16x32_bf16 v[124:127], v[148:151], v[164:167], v[124:127]
	v_mfma_f32_16x16x32_bf16 v[120:123], v[156:159], v[164:167], v[120:123]
	v_mfma_f32_16x16x32_bf16 v[108:111], v[148:151], v[192:195], v[108:111]
	v_mfma_f32_16x16x32_bf16 v[104:107], v[156:159], v[192:195], v[104:107]
	v_mfma_f32_16x16x32_bf16 v[92:95], v[148:151], v[200:203], v[92:95]
	v_mfma_f32_16x16x32_bf16 v[88:91], v[156:159], v[200:203], v[88:91]
	v_mfma_f32_16x16x32_bf16 v[76:79], v[148:151], v[214:217], v[76:79]
	v_mfma_f32_16x16x32_bf16 v[72:75], v[156:159], v[214:217], v[72:75]
	s_setprio 0
	s_barrier
	s_add_i32 s76, s76, s10
	v_lshl_add_u64 v[218:219], s[28:29], 0, v[176:177]
	s_mov_b32 m0, s76
	ds_read_b128 v[160:163], v208 offset:16384
	ds_read_b128 v[164:167], v208 offset:17408
	ds_read_b128 v[168:171], v208 offset:18432
	ds_read_b128 v[192:195], v208 offset:19456
	ds_read_b128 v[196:199], v208 offset:20480
	ds_read_b128 v[200:203], v208 offset:21504
	ds_read_b128 v[210:213], v208 offset:22528
	ds_read_b128 v[214:217], v208 offset:23552
	global_load_lds_dwordx4 v[218:219], off
	s_add_i32 m0, s76, 0x2000
	s_add_u32 s80, s28, 0x80000
	v_lshl_add_u64 v[222:223], s[28:29], 0, v[172:173]
	s_addc_u32 s81, s29, 0
	s_add_i32 s76, s77, s10
	global_load_lds_dwordx4 v[222:223], off
	v_lshl_add_u64 v[224:225], s[80:81], 0, v[176:177]
	s_mov_b32 m0, s76
	v_lshl_add_u64 v[228:229], s[30:31], 0, v[174:175]
	global_load_lds_dwordx4 v[224:225], off
	v_lshl_add_u64 v[224:225], s[80:81], 0, v[172:173]
	s_add_i32 m0, s76, 0x2000
	s_nop 0
	global_load_lds_dwordx4 v[224:225], off
	v_lshl_add_u64 v[224:225], s[30:31], 0, v[184:185]
	s_mov_b32 m0, s11
	s_nop 0
	global_load_lds_dwordx4 v[224:225], off
	s_mov_b32 m0, s25
	s_nop 0
	global_load_lds_dwordx4 v[228:229], off
	s_waitcnt vmcnt(8)
	s_waitcnt lgkmcnt(0)
	s_barrier
; #define PG8_STAGE(bufoff, gbase, voff) do { _Pragma("unroll") for (int _i = 0; _i < 2; ++_i) \
;         __builtin_amdgcn_global_load_lds((const unsigned*)((const char*)(gbase) + (voff)[_i]), (PG8_LAS unsigned*)(lds + (bufoff) + ldsw + _i * 8192), 16, 0, 0); } while (0)
; #define PG8_LDA(dst, b, h) do { _Pragma("unroll") for (int m = 0; m < 4; ++m) _Pragma("unroll") for (int k = 0; k < 2; ++k) dst[m][k] = *(const PG8_LAS bf16x8*)(lds + PG8_SA(b, h) + aoff + m * 2048 + k * 1024); } while (0)
; #define PG8_LDB(dst, b, h) do { _Pragma("unroll") for (int n = 0; n < 2; ++n) _Pragma("unroll") for (int k = 0; k < 2; ++k) dst[n][k] = *(const PG8_LAS bf16x8*)(lds + PG8_SB(b, h) + boff + n * 2048 + k * 1024); } while (0)
; #define PG8_MMA(ai, bj, At, Bt) do { __builtin_amdgcn_s_setprio(1); _Pragma("unroll") for (int m = 0; m < 4; ++m) _Pragma("unroll") for (int n = 0; n < 2; ++n) _Pragma("unroll") for (int k = 0; k < 2; ++k) \
;         acc[ai][bj][m][n] = __builtin_amdgcn_mfma_f32_16x16x32_bf16(Bt[n][k], At[m][k], acc[ai][bj][m][n], 0, 0, 0); __builtin_amdgcn_s_setprio(0); } while (0)
; #define PG8_WAIT_L(n) asm volatile("s_waitcnt lgkmcnt(" #n ")" ::: "memory")
; #define PG8_WAIT_VK do { if constexpr (HALFM) PG8_WAIT_V(6); else PG8_WAIT_V(8); } while (0)
; #define PG8_BAR __builtin_amdgcn_s_barrier()
; #define PG8_SCHED __builtin_amdgcn_sched_barrier(0)
; template <class Epi, class Sched, bool ALIGN_EPI = false, bool SP2 = false, bool HALFM = false, bool AMAP = false>
; __device__ __forceinline__ void gemm_phase(PG8_LAS unsigned char* lds, const Gemm g, const Sched& S, const Epi& E, int tid_in) {
;     ...
;             PG8_WAIT_VK; PG8_WAIT_L(0); PG8_BAR; if constexpr (!HALFM) { PG8_MMA(1, 0, At, B0); PG8_MMA(1, 1, At, B1); } PG8_BAR; PG8_SCHED;
;             PG8_LDB(B0, 1, 0); PG8_LDB(B1, 1, 1); PG8_SCHED; PG8_LDA(At, 1, 0); if constexpr (!HALFM) PG8_STAGE(PG8_SA(0, 1), a2 + hstepA, voffA);
;             PG8_WAIT_VK; PG8_WAIT_L(0); PG8_BAR; PG8_MMA(0, 0, At, B0); PG8_MMA(0, 1, At, B1); PG8_BAR; PG8_SCHED;
	s_setprio 1
	v_mfma_f32_16x16x32_bf16 v[68:71], v[0:3], v[160:163], v[68:71]
	v_mfma_f32_16x16x32_bf16 v[64:67], v[136:139], v[160:163], v[64:67]
	v_mfma_f32_16x16x32_bf16 v[52:55], v[0:3], v[168:171], v[52:55]
	v_mfma_f32_16x16x32_bf16 v[48:51], v[136:139], v[168:171], v[48:51]
	v_mfma_f32_16x16x32_bf16 v[36:39], v[0:3], v[196:199], v[36:39]
	v_mfma_f32_16x16x32_bf16 v[32:35], v[136:139], v[196:199], v[32:35]
	v_mfma_f32_16x16x32_bf16 v[0:3], v[0:3], v[210:213], v[20:23]
	v_mfma_f32_16x16x32_bf16 v[68:71], v[4:7], v[164:167], v[68:71]
	v_mfma_f32_16x16x32_bf16 v[64:67], v[140:143], v[164:167], v[64:67]
	v_mfma_f32_16x16x32_bf16 v[52:55], v[4:7], v[192:195], v[52:55]
	v_mfma_f32_16x16x32_bf16 v[48:51], v[140:143], v[192:195], v[48:51]
	v_mfma_f32_16x16x32_bf16 v[36:39], v[4:7], v[200:203], v[36:39]
	v_mfma_f32_16x16x32_bf16 v[32:35], v[140:143], v[200:203], v[32:35]
	v_mfma_f32_16x16x32_bf16 v[0:3], v[4:7], v[214:217], v[0:3]
	v_mfma_f32_16x16x32_bf16 v[4:7], v[136:139], v[210:213], v[16:19]
	v_mfma_f32_16x16x32_bf16 v[4:7], v[140:143], v[214:217], v[4:7]
	s_setprio 0
	s_setprio 1
	v_mfma_f32_16x16x32_bf16 v[16:19], v[144:147], v[160:163], v[60:63]
	v_mfma_f32_16x16x32_bf16 v[60:63], v[148:151], v[164:167], v[16:19]
	v_mfma_f32_16x16x32_bf16 v[16:19], v[152:155], v[160:163], v[56:59]
	v_mfma_f32_16x16x32_bf16 v[56:59], v[156:159], v[164:167], v[16:19]
	v_mfma_f32_16x16x32_bf16 v[16:19], v[144:147], v[168:171], v[44:47]
	v_mfma_f32_16x16x32_bf16 v[44:47], v[148:151], v[192:195], v[16:19]
	v_mfma_f32_16x16x32_bf16 v[16:19], v[152:155], v[168:171], v[40:43]
	v_mfma_f32_16x16x32_bf16 v[40:43], v[156:159], v[192:195], v[16:19]
	v_mfma_f32_16x16x32_bf16 v[16:19], v[144:147], v[196:199], v[28:31]
	v_mfma_f32_16x16x32_bf16 v[28:31], v[148:151], v[200:203], v[16:19]
	v_mfma_f32_16x16x32_bf16 v[16:19], v[152:155], v[196:199], v[24:27]
	v_mfma_f32_16x16x32_bf16 v[12:15], v[144:147], v[210:213], v[12:15]
	v_mfma_f32_16x16x32_bf16 v[8:11], v[152:155], v[210:213], v[8:11]
	v_mfma_f32_16x16x32_bf16 v[24:27], v[156:159], v[200:203], v[16:19]
	v_mfma_f32_16x16x32_bf16 v[12:15], v[148:151], v[214:217], v[12:15]
	v_mfma_f32_16x16x32_bf16 v[8:11], v[156:159], v[214:217], v[8:11]
	s_setprio 0
	s_barrier
	s_add_i32 s76, 0, 0x18000
	s_add_i32 s77, 0, 0x1c000
	v_add_u32_e32 v140, s76, v205
	v_add_u32_e32 v156, s77, v205
	ds_read_b128 v[16:19], v140
	ds_read_b128 v[20:23], v140 offset:1024
	ds_read_b128 v[136:139], v140 offset:2048
	ds_read_b128 v[140:143], v140 offset:3072
	ds_read_b128 v[144:147], v156
	ds_read_b128 v[148:151], v156 offset:1024
	ds_read_b128 v[152:155], v156 offset:2048
	ds_read_b128 v[156:159], v156 offset:3072
	s_add_u32 s30, s30, 0x80000
	s_addc_u32 s31, s31, 0
	s_mov_b32 m0, s36
	v_lshl_add_u64 v[230:231], s[30:31], 0, v[184:185]
	ds_read_b128 v[160:163], v208 offset:32768
	ds_read_b128 v[164:167], v208 offset:33792
	ds_read_b128 v[168:171], v208 offset:34816
	ds_read_b128 v[192:195], v208 offset:35840
	ds_read_b128 v[196:199], v208 offset:36864
	ds_read_b128 v[200:203], v208 offset:37888
	ds_read_b128 v[210:213], v208 offset:38912
	ds_read_b128 v[214:217], v208 offset:39936
	global_load_lds_dwordx4 v[230:231], off
	v_lshl_add_u64 v[230:231], s[30:31], 0, v[174:175]
	s_mov_b32 m0, s37
	s_nop 0
	global_load_lds_dwordx4 v[230:231], off
	s_waitcnt vmcnt(8)
	s_waitcnt lgkmcnt(0)
	s_barrier
	s_setprio 1
	v_mfma_f32_16x16x32_bf16 v[132:135], v[16:19], v[160:163], v[132:135]
	v_mfma_f32_16x16x32_bf16 v[128:131], v[136:139], v[160:163], v[128:131]
	v_mfma_f32_16x16x32_bf16 v[116:119], v[16:19], v[168:171], v[116:119]
	v_mfma_f32_16x16x32_bf16 v[112:115], v[136:139], v[168:171], v[112:115]
	v_mfma_f32_16x16x32_bf16 v[100:103], v[16:19], v[196:199], v[100:103]
	v_mfma_f32_16x16x32_bf16 v[96:99], v[136:139], v[196:199], v[96:99]
	v_mfma_f32_16x16x32_bf16 v[84:87], v[16:19], v[210:213], v[84:87]
	v_mfma_f32_16x16x32_bf16 v[80:83], v[136:139], v[210:213], v[80:83]
	v_mfma_f32_16x16x32_bf16 v[132:135], v[20:23], v[164:167], v[132:135]
	v_mfma_f32_16x16x32_bf16 v[128:131], v[140:143], v[164:167], v[128:131]
	v_mfma_f32_16x16x32_bf16 v[116:119], v[20:23], v[192:195], v[116:119]
	v_mfma_f32_16x16x32_bf16 v[112:115], v[140:143], v[192:195], v[112:115]
	v_mfma_f32_16x16x32_bf16 v[100:103], v[20:23], v[200:203], v[100:103]
	v_mfma_f32_16x16x32_bf16 v[96:99], v[140:143], v[200:203], v[96:99]
	v_mfma_f32_16x16x32_bf16 v[84:87], v[20:23], v[214:217], v[84:87]
	v_mfma_f32_16x16x32_bf16 v[80:83], v[140:143], v[214:217], v[80:83]
	s_setprio 0
	s_setprio 1
	v_mfma_f32_16x16x32_bf16 v[124:127], v[144:147], v[160:163], v[124:127]
	v_mfma_f32_16x16x32_bf16 v[120:123], v[152:155], v[160:163], v[120:123]
	v_mfma_f32_16x16x32_bf16 v[108:111], v[144:147], v[168:171], v[108:111]
	v_mfma_f32_16x16x32_bf16 v[104:107], v[152:155], v[168:171], v[104:107]
	v_mfma_f32_16x16x32_bf16 v[92:95], v[144:147], v[196:199], v[92:95]
	v_mfma_f32_16x16x32_bf16 v[88:91], v[152:155], v[196:199], v[88:91]
	v_mfma_f32_16x16x32_bf16 v[76:79], v[144:147], v[210:213], v[76:79]
	v_mfma_f32_16x16x32_bf16 v[72:75], v[152:155], v[210:213], v[72:75]
	v_mfma_f32_16x16x32_bf16 v[124:127], v[148:151], v[164:167], v[124:127]
	v_mfma_f32_16x16x32_bf16 v[120:123], v[156:159], v[164:167], v[120:123]
	v_mfma_f32_16x16x32_bf16 v[108:111], v[148:151], v[192:195], v[108:111]
	v_mfma_f32_16x16x32_bf16 v[104:107], v[156:159], v[192:195], v[104:107]
	v_mfma_f32_16x16x32_bf16 v[92:95], v[148:151], v[200:203], v[92:95]
	v_mfma_f32_16x16x32_bf16 v[88:91], v[156:159], v[200:203], v[88:91]
	v_mfma_f32_16x16x32_bf16 v[76:79], v[148:151], v[214:217], v[76:79]
	v_mfma_f32_16x16x32_bf16 v[72:75], v[156:159], v[214:217], v[72:75]
	s_setprio 0
	s_barrier
; #define PG8_LAS __attribute__((address_space(3)))
; #define PG8_STAGE(bufoff, gbase, voff) do { _Pragma("unroll") for (int _i = 0; _i < 2; ++_i) \
;         __builtin_amdgcn_global_load_lds((const unsigned*)((const char*)(gbase) + (voff)[_i]), (PG8_LAS unsigned*)(lds + (bufoff) + ldsw + _i * 8192), 16, 0, 0); } while (0)
; #define PG8_LDA(dst, b, h) do { _Pragma("unroll") for (int m = 0; m < 4; ++m) _Pragma("unroll") for (int k = 0; k < 2; ++k) dst[m][k] = *(const PG8_LAS bf16x8*)(lds + PG8_SA(b, h) + aoff + m * 2048 + k * 1024); } while (0)
; #define PG8_WAIT_L(n) asm volatile("s_waitcnt lgkmcnt(" #n ")" ::: "memory")
; #define PG8_WAIT_VK do { if constexpr (HALFM) PG8_WAIT_V(6); else PG8_WAIT_V(8); } while (0)
; #define PG8_BAR __builtin_amdgcn_s_barrier()
; template <bool TOK = false> __device__ __forceinline__ void rows_rstd(float (&rs)[8], const float* ssq, int row0, int fq) {
;     f32x4 pa[8], pb[8];
; #pragma unroll
;     for (int i = 0; i < 8; ++i) { const f32x4* p = (const f32x4*)(ssq + (size_t)(TOK ? row0 + 64 * i : row0 + (i >> 2) * HALF + (i & 3) * 16) * 32 + fq * 8); pa[i] = p[0]; pb[i] = p[1]; }
;     __builtin_amdgcn_sched_barrier(0);
;     __device__ __forceinline__ void operator()(const f32x4 (&acc)[2][2][4][2], const Unit& u, int wr, int wc, int fr, int fq, const PG8_LAS float* rc, bool cached) const {
;     ...
;         if (cached) {
; #pragma unroll
;             for (int i = 0; i < (HALFM ? 4 : 8); ++i) rsv[i] = rc[(i >> 2) * HALF + wr * 64 + (i & 3) * 16 + fr + z];
;         } else rows_rstd<false>(rsv, ssq, row0, fq);
; template <class Epi, class Sched, bool ALIGN_EPI = false, bool SP2 = false, bool HALFM = false, bool AMAP = false>
; __device__ __forceinline__ void gemm_phase(PG8_LAS unsigned char* lds, const Gemm g, const Sched& S, const Epi& E, int tid_in) {
;     ...
;             if constexpr (!HALFM) { PG8_LDA(At, 1, 1); } PG8_STAGE(PG8_SB(1, 0), b3, voffB); PG8_STAGE(PG8_SB(1, 1), b3 + hstepB, voffB); PG8_STAGE(PG8_SA(1, 0), a3, voffA);
;             PG8_WAIT_VK; PG8_WAIT_L(0); PG8_BAR; if constexpr (!HALFM) { PG8_MMA(1, 0, At, B0); PG8_MMA(1, 1, At, B1); } PG8_BAR; PG8_SCHED;
;     ...
;         if constexpr (ALIGN_EPI) { if (wr == 0) PG8_BAR; }
;         if constexpr (!Epi::AFTER_DRAIN) { if constexpr (Epi::RSTD) E(acc, cur, wr, wc, fr, fq, (const PG8_LAS float*)(lds + STAGE_BYTES), cur.pm == pm0); else E(acc, cur, wr, wc, fr, fq); S.done(cur); }
	s_add_i32 s30, s76, s10
	v_lshl_add_u64 v[218:219], v[218:219], 0, s[66:67]
	s_mov_b32 m0, s30
	ds_read_b128 v[160:163], v208 offset:49152
	ds_read_b128 v[164:167], v208 offset:50176
	ds_read_b128 v[168:171], v208 offset:51200
	ds_read_b128 v[192:195], v208 offset:52224
	ds_read_b128 v[196:199], v208 offset:53248
	ds_read_b128 v[200:203], v208 offset:54272
	ds_read_b128 v[210:213], v208 offset:55296
	ds_read_b128 v[214:217], v208 offset:56320
	global_load_lds_dwordx4 v[218:219], off
	s_add_i32 m0, s30, 0x2000
	s_add_u32 s28, s28, 0x80080
	v_lshl_add_u64 v[218:219], v[222:223], 0, s[66:67]
	s_addc_u32 s29, s29, 0
	s_add_i32 s30, s77, s10
	global_load_lds_dwordx4 v[218:219], off
	v_lshl_add_u64 v[218:219], s[28:29], 0, v[176:177]
	s_mov_b32 m0, s30
	s_nop 0
	global_load_lds_dwordx4 v[218:219], off
	v_lshl_add_u64 v[218:219], s[28:29], 0, v[172:173]
	s_add_i32 m0, s30, 0x2000
	s_nop 0
	global_load_lds_dwordx4 v[218:219], off
	v_lshl_add_u64 v[218:219], v[224:225], 0, s[66:67]
	s_mov_b32 m0, s38
	s_nop 0
	global_load_lds_dwordx4 v[218:219], off
	v_lshl_add_u64 v[218:219], v[228:229], 0, s[66:67]
	s_mov_b32 m0, s39
	s_nop 0
	global_load_lds_dwordx4 v[218:219], off
	s_waitcnt vmcnt(8)
	s_waitcnt lgkmcnt(0)
	s_barrier
	s_setprio 1
	v_mfma_f32_16x16x32_bf16 v[68:71], v[16:19], v[160:163], v[68:71]
	v_mfma_f32_16x16x32_bf16 v[52:55], v[16:19], v[168:171], v[52:55]
	v_mfma_f32_16x16x32_bf16 v[36:39], v[16:19], v[196:199], v[36:39]
	v_mfma_f32_16x16x32_bf16 v[0:3], v[16:19], v[210:213], v[0:3]
	v_mfma_f32_16x16x32_bf16 v[68:71], v[20:23], v[164:167], v[68:71]
	v_mfma_f32_16x16x32_bf16 v[64:67], v[136:139], v[160:163], v[64:67]
	v_mfma_f32_16x16x32_bf16 v[52:55], v[20:23], v[192:195], v[52:55]
	v_mfma_f32_16x16x32_bf16 v[48:51], v[136:139], v[168:171], v[48:51]
	v_mfma_f32_16x16x32_bf16 v[36:39], v[20:23], v[200:203], v[36:39]
	v_mfma_f32_16x16x32_bf16 v[32:35], v[136:139], v[196:199], v[32:35]
	v_mfma_f32_16x16x32_bf16 v[20:23], v[20:23], v[214:217], v[0:3]
	v_mfma_f32_16x16x32_bf16 v[0:3], v[136:139], v[210:213], v[4:7]
	v_mfma_f32_16x16x32_bf16 v[64:67], v[140:143], v[164:167], v[64:67]
	v_mfma_f32_16x16x32_bf16 v[48:51], v[140:143], v[192:195], v[48:51]
	v_mfma_f32_16x16x32_bf16 v[32:35], v[140:143], v[200:203], v[32:35]
	v_mfma_f32_16x16x32_bf16 v[16:19], v[140:143], v[214:217], v[0:3]
	s_setprio 0
	s_setprio 1
	v_mfma_f32_16x16x32_bf16 v[0:3], v[144:147], v[160:163], v[60:63]
	v_mfma_f32_16x16x32_bf16 v[60:63], v[148:151], v[164:167], v[0:3]
	v_mfma_f32_16x16x32_bf16 v[0:3], v[152:155], v[160:163], v[56:59]
	v_mfma_f32_16x16x32_bf16 v[56:59], v[156:159], v[164:167], v[0:3]
	v_mfma_f32_16x16x32_bf16 v[0:3], v[144:147], v[168:171], v[44:47]
	v_mfma_f32_16x16x32_bf16 v[44:47], v[148:151], v[192:195], v[0:3]
	v_mfma_f32_16x16x32_bf16 v[0:3], v[152:155], v[168:171], v[40:43]
	v_mfma_f32_16x16x32_bf16 v[40:43], v[156:159], v[192:195], v[0:3]
	v_mfma_f32_16x16x32_bf16 v[0:3], v[144:147], v[196:199], v[28:31]
	v_mfma_f32_16x16x32_bf16 v[28:31], v[148:151], v[200:203], v[0:3]
	v_mfma_f32_16x16x32_bf16 v[0:3], v[152:155], v[196:199], v[24:27]
	v_mfma_f32_16x16x32_bf16 v[24:27], v[156:159], v[200:203], v[0:3]
	v_mfma_f32_16x16x32_bf16 v[0:3], v[144:147], v[210:213], v[12:15]
	v_mfma_f32_16x16x32_bf16 v[12:15], v[148:151], v[214:217], v[0:3]
	v_mfma_f32_16x16x32_bf16 v[0:3], v[152:155], v[210:213], v[8:11]
	v_mfma_f32_16x16x32_bf16 v[8:11], v[156:159], v[214:217], v[0:3]
	s_setprio 0
	s_barrier
	s_add_i32 s63, s63, 2
	s_add_u32 s61, s61, 0x100
	s_addc_u32 s62, s62, 0
	s_add_u32 s6, s6, 0x100
	s_addc_u32 s7, s7, 0
	s_cmp_gt_u32 s63, 29
	s_cbranch_scc0 .LBB0_163
.LBB0_166:
	s_lshl_b32 s6, s58, 8
	v_mov_b32 v209, 0
	s_cmp_lg_u32 s58, s26
	v_add3_u32 v200, s6, v204, v209
	v_add_u32_e32 v198, 16, v200
	v_add_u32_e32 v196, 32, v200
	v_add_u32_e32 v194, 48, v200
	s_mov_b64 s[6:7], -1
	v_ashrrev_i32_e32 v201, 31, v200
	v_ashrrev_i32_e32 v199, 31, v198
	v_ashrrev_i32_e32 v197, 31, v196
	v_ashrrev_i32_e32 v195, 31, v194
	v_add_u32_e32 v202, 0x80, v200
	s_cbranch_scc0 .LBB0_168
	v_lshlrev_b64 v[0:1], 7, v[200:201]
	v_lshlrev_b64 v[4:5], 7, v[198:199]
	v_lshl_add_u64 v[136:137], v[186:187], 0, v[0:1]
	v_lshl_add_u64 v[4:5], v[186:187], 0, v[4:5]
	global_load_dwordx4 v[0:3], v[136:137], off
	global_load_dwordx4 v[210:213], v[136:137], off offset:16
	global_load_dwordx4 v[214:217], v[4:5], off
	global_load_dwordx4 v[222:225], v[4:5], off offset:16
	v_lshlrev_b64 v[4:5], 7, v[196:197]
	v_lshl_add_u64 v[4:5], v[186:187], 0, v[4:5]
	global_load_dwordx4 v[232:235], v[4:5], off
	global_load_dwordx4 v[236:239], v[4:5], off offset:16
	v_lshlrev_b64 v[4:5], 7, v[194:195]
	v_add_u32_e32 v192, 0x80, v200
	v_lshl_add_u64 v[4:5], v[186:187], 0, v[4:5]
	v_ashrrev_i32_e32 v193, 31, v192
	global_load_dwordx4 v[168:171], v[4:5], off
	global_load_dwordx4 v[164:167], v[4:5], off offset:16
	v_lshlrev_b64 v[4:5], 7, v[192:193]
	v_add_co_u32_e32 v140, vcc, s87, v136
	v_lshl_add_u64 v[4:5], v[186:187], 0, v[4:5]
	s_nop 0
	v_addc_co_u32_e32 v141, vcc, 0, v137, vcc
	global_load_dwordx4 v[160:163], v[4:5], off
	s_nop 0
	global_load_dwordx4 v[4:7], v[4:5], off offset:16
	v_lshl_add_u64 v[138:139], v[136:137], 0, s[70:71]
	global_load_dwordx4 v[156:159], v[140:141], off offset:2048
	global_load_dwordx4 v[152:155], v[138:139], off offset:16
	v_add_co_u32_e32 v140, vcc, s56, v136
	v_lshl_add_u64 v[138:139], v[136:137], 0, s[72:73]
	s_nop 0
	v_addc_co_u32_e32 v141, vcc, 0, v137, vcc
	v_lshl_add_u64 v[136:137], v[136:137], 0, s[74:75]
	global_load_dwordx4 v[148:151], v[140:141], off
	global_load_dwordx4 v[144:147], v[138:139], off offset:16
	s_nop 0
	global_load_dwordx4 v[140:143], v[140:141], off offset:2048
	s_nop 0
	global_load_dwordx4 v[136:139], v[136:137], off offset:16
	s_waitcnt vmcnt(0)
; __device__ __forceinline__ float sum_xor16(float v) { float a = v, b = v; asm volatile("s_nop 1\n\tv_permlane16_swap_b32 %0, %1" : "+v"(a), "+v"(b)); return a + b; }
; __device__ __forceinline__ float sum_xor32(float v) { float a = v, b = v; asm volatile("s_nop 1\n\tv_permlane32_swap_b32 %0, %1" : "+v"(a), "+v"(b)); return a + b; }
; __device__ __forceinline__ float sum_fq(float s) { return sum_xor32(sum_xor16(s)); }
; template <bool TOK = false> __device__ __forceinline__ void rows_rstd(float (&rs)[8], const float* ssq, int row0, int fq) {
;     f32x4 pa[8], pb[8];
; #pragma unroll
;     for (int i = 0; i < 8; ++i) { const f32x4* p = (const f32x4*)(ssq + (size_t)(TOK ? row0 + 64 * i : row0 + (i >> 2) * HALF + (i & 3) * 16) * 32 + fq * 8); pa[i] = p[0]; pb[i] = p[1]; }
;     __builtin_amdgcn_sched_barrier(0);
; #pragma unroll
;     for (int i = 0; i < 8; ++i) { const f32x4 a = pa[i], b = pb[i]; float s = ((a[0] + a[1]) + (a[2] + a[3])) + ((b[0] + b[1]) + (b[2] + b[3])); s = sum_fq(s); rs[i] = 1.0f / sqrtf(s * (1.0f / 2048.0f) + 1e-6f); }
; }
	v_mov_b32_e32 v218, v0
	v_mov_b32_e32 v219, v210
	v_mov_b32_e32 v210, v1
	v_pk_add_f32 v[0:1], v[218:219], v[210:211]
	v_mov_b32_e32 v210, v2
	v_mov_b32_e32 v211, v212
	v_mov_b32_e32 v212, v3
	v_pk_add_f32 v[2:3], v[210:211], v[212:213]
	v_mov_b32_e32 v210, v216
	v_pk_add_f32 v[0:1], v[0:1], v[2:3]
	v_mov_b32_e32 v211, v224
	v_add_f32_e32 v0, v0, v1
	v_mov_b32_e32 v1, v0
	s_nop 1
	v_permlane16_swap_b32 v0, v1
	v_mov_b32_e32 v224, v217
	v_add_f32_e32 v0, v0, v1
	v_mov_b32_e32 v1, v0
	s_nop 1
	v_permlane32_swap_b32 v0, v1
	v_pk_add_f32 v[210:211], v[210:211], v[224:225]
	v_add_f32_e32 v0, v0, v1
	v_fmamk_f32 v0, v0, 0x3a000000, v221
	v_cmp_gt_f32_e32 vcc, s52, v0
	v_mul_f32_e32 v1, 0x4f800000, v0
	s_nop 0
	v_cndmask_b32_e32 v0, v0, v1, vcc
	v_sqrt_f32_e32 v1, v0
	s_nop 0
	v_add_u32_e32 v2, -1, v1
	v_fma_f32 v3, -v2, v1, v0
	v_cmp_ge_f32_e64 s[6:7], 0, v3
	v_add_u32_e32 v3, 1, v1
	s_nop 0
	v_cndmask_b32_e64 v2, v1, v2, s[6:7]
	v_fma_f32 v1, -v3, v1, v0
	v_cmp_lt_f32_e64 s[6:7], 0, v1
	s_nop 1
	v_cndmask_b32_e64 v1, v2, v3, s[6:7]
	v_mul_f32_e32 v2, 0x37800000, v1
	v_cndmask_b32_e32 v1, v1, v2, vcc
	v_cmp_class_f32_e32 vcc, v0, v226
	s_nop 1
	v_cndmask_b32_e32 v0, v1, v0, vcc
	v_div_scale_f32 v1, s[6:7], v0, v0, 1.0
	v_rcp_f32_e32 v2, v1
	s_nop 0
	v_fma_f32 v3, -v1, v2, 1.0
	v_fmac_f32_e32 v2, v3, v2
	v_div_scale_f32 v3, vcc, 1.0, v0, 1.0
	v_mul_f32_e32 v178, v3, v2
	v_fma_f32 v179, -v1, v178, v3
	v_fmac_f32_e32 v178, v179, v2
	v_fma_f32 v1, -v1, v178, v3
	v_div_fmas_f32 v1, v1, v2, v178
	v_mov_b32_e32 v2, v214
	v_mov_b32_e32 v3, v222
	v_mov_b32_e32 v222, v215
	v_pk_add_f32 v[2:3], v[2:3], v[222:223]
	v_div_fixup_f32 v0, v1, v0, 1.0
	v_pk_add_f32 v[2:3], v[2:3], v[210:211]
	v_mov_b32_e32 v210, v234
	v_add_f32_e32 v1, v2, v3
	v_mov_b32_e32 v2, v1
	s_nop 1
	v_permlane16_swap_b32 v2, v1
	v_mov_b32_e32 v211, v238
	v_add_f32_e32 v1, v2, v1
	v_mov_b32_e32 v2, v1
	s_nop 1
	v_permlane32_swap_b32 v2, v1
	v_mov_b32_e32 v238, v235
	v_add_f32_e32 v1, v2, v1
	v_fmamk_f32 v1, v1, 0x3a000000, v221
	v_cmp_gt_f32_e32 vcc, s52, v1
	v_mul_f32_e32 v2, 0x4f800000, v1
	v_pk_add_f32 v[210:211], v[210:211], v[238:239]
	v_cndmask_b32_e32 v1, v1, v2, vcc
	v_sqrt_f32_e32 v2, v1
	s_nop 0
	v_add_u32_e32 v3, -1, v2
	v_fma_f32 v178, -v3, v2, v1
	v_cmp_ge_f32_e64 s[6:7], 0, v178
	v_add_u32_e32 v178, 1, v2
	s_nop 0
	v_cndmask_b32_e64 v3, v2, v3, s[6:7]
	v_fma_f32 v2, -v178, v2, v1
	v_cmp_lt_f32_e64 s[6:7], 0, v2
	s_nop 1
	v_cndmask_b32_e64 v2, v3, v178, s[6:7]
	v_mul_f32_e32 v3, 0x37800000, v2
	v_cndmask_b32_e32 v2, v2, v3, vcc
	v_cmp_class_f32_e32 vcc, v1, v226
	s_nop 1
	v_cndmask_b32_e32 v1, v2, v1, vcc
	v_div_scale_f32 v2, s[6:7], v1, v1, 1.0
	v_rcp_f32_e32 v3, v2
	s_nop 0
	v_fma_f32 v178, -v2, v3, 1.0
	v_fmac_f32_e32 v3, v178, v3
	v_div_scale_f32 v178, vcc, 1.0, v1, 1.0
	v_mul_f32_e32 v179, v178, v3
	v_fma_f32 v180, -v2, v179, v178
	v_fmac_f32_e32 v179, v180, v3
	v_fma_f32 v2, -v2, v179, v178
	v_div_fmas_f32 v2, v2, v3, v179
	v_div_fixup_f32 v1, v2, v1, 1.0
	v_mov_b32_e32 v2, v232
	v_mov_b32_e32 v3, v236
	v_mov_b32_e32 v236, v233
	v_pk_add_f32 v[2:3], v[2:3], v[236:237]
	s_nop 0
	v_pk_add_f32 v[2:3], v[2:3], v[210:211]
	v_mov_b32_e32 v210, v168
	v_add_f32_e32 v2, v2, v3
	v_mov_b32_e32 v3, v2
	s_nop 1
	v_permlane16_swap_b32 v2, v3
	v_mov_b32_e32 v211, v164
	v_add_f32_e32 v2, v2, v3
	v_mov_b32_e32 v3, v2
	s_nop 1
	v_permlane32_swap_b32 v3, v2
	v_mov_b32_e32 v164, v169
	v_add_f32_e32 v2, v3, v2
	v_fmamk_f32 v2, v2, 0x3a000000, v221
	v_cmp_gt_f32_e32 vcc, s52, v2
	v_mul_f32_e32 v3, 0x4f800000, v2
	v_mov_b32_e32 v168, v170
	v_cndmask_b32_e32 v2, v2, v3, vcc
	v_sqrt_f32_e32 v3, v2
	v_mov_b32_e32 v169, v166
	v_mov_b32_e32 v166, v171
	v_pk_add_f32 v[164:165], v[210:211], v[164:165]
	v_add_u32_e32 v178, -1, v3
	v_fma_f32 v179, -v178, v3, v2
	v_cmp_ge_f32_e64 s[6:7], 0, v179
	v_add_u32_e32 v179, 1, v3
	v_pk_add_f32 v[166:167], v[168:169], v[166:167]
	v_cndmask_b32_e64 v178, v3, v178, s[6:7]
	v_fma_f32 v3, -v179, v3, v2
	v_cmp_lt_f32_e64 s[6:7], 0, v3
	v_pk_add_f32 v[164:165], v[164:165], v[166:167]
	s_nop 0
	v_cndmask_b32_e64 v3, v178, v179, s[6:7]
	v_mul_f32_e32 v178, 0x37800000, v3
	v_cndmask_b32_e32 v3, v3, v178, vcc
	v_cmp_class_f32_e32 vcc, v2, v226
	s_nop 1
	v_cndmask_b32_e32 v2, v3, v2, vcc
	v_div_scale_f32 v3, s[6:7], v2, v2, 1.0
	v_rcp_f32_e32 v178, v3
	s_nop 0
	v_fma_f32 v179, -v3, v178, 1.0
	v_fmac_f32_e32 v178, v179, v178
	v_div_scale_f32 v179, vcc, 1.0, v2, 1.0
	v_mul_f32_e32 v180, v179, v178
	v_fma_f32 v181, -v3, v180, v179
	v_fmac_f32_e32 v180, v181, v178
	v_fma_f32 v3, -v3, v180, v179
	v_div_fmas_f32 v3, v3, v178, v180
	v_div_fixup_f32 v2, v3, v2, 1.0
	v_add_f32_e32 v3, v164, v165
	v_mov_b32_e32 v164, v3
	s_nop 1
	v_permlane16_swap_b32 v164, v3
	s_nop 0
	v_add_f32_e32 v3, v164, v3
	v_mov_b32_e32 v164, v3
	s_nop 1
	v_permlane32_swap_b32 v3, v164
	s_nop 0
	v_add_f32_e32 v3, v3, v164
	v_fmamk_f32 v3, v3, 0x3a000000, v221
	v_cmp_gt_f32_e32 vcc, s52, v3
	v_mul_f32_e32 v164, 0x4f800000, v3
	s_nop 0
	v_cndmask_b32_e32 v3, v3, v164, vcc
	v_sqrt_f32_e32 v164, v3
	s_nop 0
	v_add_u32_e32 v165, -1, v164
	v_fma_f32 v166, -v165, v164, v3
	v_cmp_ge_f32_e64 s[6:7], 0, v166
	v_add_u32_e32 v166, 1, v164
	s_nop 0
	v_cndmask_b32_e64 v165, v164, v165, s[6:7]
	v_fma_f32 v164, -v166, v164, v3
	v_cmp_lt_f32_e64 s[6:7], 0, v164
	s_nop 1
	v_cndmask_b32_e64 v164, v165, v166, s[6:7]
	v_mul_f32_e32 v165, 0x37800000, v164
	v_cndmask_b32_e32 v164, v164, v165, vcc
	v_cmp_class_f32_e32 vcc, v3, v226
	s_nop 1
	v_cndmask_b32_e32 v3, v164, v3, vcc
	v_div_scale_f32 v164, s[6:7], v3, v3, 1.0
	v_rcp_f32_e32 v165, v164
	s_nop 0
	v_fma_f32 v166, -v164, v165, 1.0
	v_fmac_f32_e32 v165, v166, v165
; __device__ __forceinline__ float sum_xor16(float v) { float a = v, b = v; asm volatile("s_nop 1\n\tv_permlane16_swap_b32 %0, %1" : "+v"(a), "+v"(b)); return a + b; }
; __device__ __forceinline__ float sum_xor32(float v) { float a = v, b = v; asm volatile("s_nop 1\n\tv_permlane32_swap_b32 %0, %1" : "+v"(a), "+v"(b)); return a + b; }
; __device__ __forceinline__ float sum_fq(float s) { return sum_xor32(sum_xor16(s)); }
; template <bool TOK = false> __device__ __forceinline__ void rows_rstd(float (&rs)[8], const float* ssq, int row0, int fq) {
;     f32x4 pa[8], pb[8];
; #pragma unroll
;     for (int i = 0; i < 8; ++i) { const f32x4* p = (const f32x4*)(ssq + (size_t)(TOK ? row0 + 64 * i : row0 + (i >> 2) * HALF + (i & 3) * 16) * 32 + fq * 8); pa[i] = p[0]; pb[i] = p[1]; }
;     __builtin_amdgcn_sched_barrier(0);
; #pragma unroll
;     for (int i = 0; i < 8; ++i) { const f32x4 a = pa[i], b = pb[i]; float s = ((a[0] + a[1]) + (a[2] + a[3])) + ((b[0] + b[1]) + (b[2] + b[3])); s = sum_fq(s); rs[i] = 1.0f / sqrtf(s * (1.0f / 2048.0f) + 1e-6f); }
; }
	v_div_scale_f32 v166, vcc, 1.0, v3, 1.0
	v_mul_f32_e32 v167, v166, v165
	v_fma_f32 v168, -v164, v167, v166
	v_fmac_f32_e32 v167, v168, v165
	v_fma_f32 v164, -v164, v167, v166
	v_div_fmas_f32 v164, v164, v165, v167
	v_div_fixup_f32 v3, v164, v3, 1.0
	v_mov_b32_e32 v164, v160
	v_mov_b32_e32 v165, v4
	v_mov_b32_e32 v4, v161
	v_mov_b32_e32 v160, v162
	v_mov_b32_e32 v161, v6
	v_mov_b32_e32 v6, v163
	v_pk_add_f32 v[4:5], v[164:165], v[4:5]
	v_pk_add_f32 v[6:7], v[160:161], v[6:7]
	s_nop 0
	v_pk_add_f32 v[4:5], v[4:5], v[6:7]
	s_nop 0
	v_add_f32_e32 v4, v4, v5
	v_mov_b32_e32 v5, v4
	s_nop 1
	v_permlane16_swap_b32 v5, v4
	s_nop 0
	v_add_f32_e32 v4, v5, v4
	v_mov_b32_e32 v5, v4
	s_nop 1
	v_permlane32_swap_b32 v5, v4
	s_nop 0
	v_add_f32_e32 v4, v5, v4
	v_fmamk_f32 v4, v4, 0x3a000000, v221
	v_cmp_gt_f32_e32 vcc, s52, v4
	v_mul_f32_e32 v5, 0x4f800000, v4
	s_nop 0
	v_cndmask_b32_e32 v4, v4, v5, vcc
	v_sqrt_f32_e32 v5, v4
	s_nop 0
	v_add_u32_e32 v6, -1, v5
	v_fma_f32 v7, -v6, v5, v4
	v_cmp_ge_f32_e64 s[6:7], 0, v7
	v_add_u32_e32 v7, 1, v5
	s_nop 0
	v_cndmask_b32_e64 v6, v5, v6, s[6:7]
	v_fma_f32 v5, -v7, v5, v4
	v_cmp_lt_f32_e64 s[6:7], 0, v5
	s_nop 1
	v_cndmask_b32_e64 v5, v6, v7, s[6:7]
	v_mul_f32_e32 v6, 0x37800000, v5
	v_cndmask_b32_e32 v5, v5, v6, vcc
	v_cmp_class_f32_e32 vcc, v4, v226
	s_nop 1
	v_cndmask_b32_e32 v4, v5, v4, vcc
	v_div_scale_f32 v5, s[6:7], v4, v4, 1.0
	v_rcp_f32_e32 v6, v5
	s_nop 0
	v_fma_f32 v7, -v5, v6, 1.0
	v_fmac_f32_e32 v6, v7, v6
	v_div_scale_f32 v7, vcc, 1.0, v4, 1.0
	v_mul_f32_e32 v160, v7, v6
	v_fma_f32 v161, -v5, v160, v7
	v_fmac_f32_e32 v160, v161, v6
	v_fma_f32 v5, -v5, v160, v7
	v_div_fmas_f32 v5, v5, v6, v160
	v_mov_b32_e32 v6, v156
	v_mov_b32_e32 v7, v152
	v_mov_b32_e32 v152, v157
	v_pk_add_f32 v[6:7], v[6:7], v[152:153]
	v_mov_b32_e32 v152, v158
	v_mov_b32_e32 v153, v154
	v_mov_b32_e32 v154, v159
	v_pk_add_f32 v[152:153], v[152:153], v[154:155]
	v_div_fixup_f32 v4, v5, v4, 1.0
	v_pk_add_f32 v[6:7], v[6:7], v[152:153]
	s_nop 0
	v_add_f32_e32 v5, v6, v7
	v_mov_b32_e32 v6, v5
	s_nop 1
	v_permlane16_swap_b32 v5, v6
	s_nop 0
	v_add_f32_e32 v5, v5, v6
	v_mov_b32_e32 v6, v5
	s_nop 1
	v_permlane32_swap_b32 v6, v5
	s_nop 0
	v_add_f32_e32 v5, v6, v5
	v_fmamk_f32 v5, v5, 0x3a000000, v221
	v_cmp_gt_f32_e32 vcc, s52, v5
	v_mul_f32_e32 v6, 0x4f800000, v5
	s_nop 0
	v_cndmask_b32_e32 v5, v5, v6, vcc
	v_sqrt_f32_e32 v6, v5
	s_nop 0
	v_add_u32_e32 v7, -1, v6
	v_fma_f32 v152, -v7, v6, v5
	v_cmp_ge_f32_e64 s[6:7], 0, v152
	v_add_u32_e32 v152, 1, v6
	s_nop 0
	v_cndmask_b32_e64 v7, v6, v7, s[6:7]
	v_fma_f32 v6, -v152, v6, v5
	v_cmp_lt_f32_e64 s[6:7], 0, v6
	s_nop 1
	v_cndmask_b32_e64 v6, v7, v152, s[6:7]
	v_mul_f32_e32 v7, 0x37800000, v6
	v_cndmask_b32_e32 v6, v6, v7, vcc
	v_cmp_class_f32_e32 vcc, v5, v226
	s_nop 1
	v_cndmask_b32_e32 v5, v6, v5, vcc
	v_div_scale_f32 v6, s[6:7], v5, v5, 1.0
	v_rcp_f32_e32 v7, v6
	s_nop 0
	v_fma_f32 v152, -v6, v7, 1.0
	v_fmac_f32_e32 v7, v152, v7
	v_div_scale_f32 v152, vcc, 1.0, v5, 1.0
	v_mul_f32_e32 v153, v152, v7
	v_fma_f32 v154, -v6, v153, v152
	v_fmac_f32_e32 v153, v154, v7
	v_fma_f32 v6, -v6, v153, v152
	v_div_fmas_f32 v6, v6, v7, v153
	v_div_fixup_f32 v5, v6, v5, 1.0
	v_mov_b32_e32 v6, v148
	v_mov_b32_e32 v7, v144
	v_mov_b32_e32 v144, v149
	v_pk_add_f32 v[6:7], v[6:7], v[144:145]
	v_mov_b32_e32 v144, v150
	v_mov_b32_e32 v145, v146
	v_mov_b32_e32 v146, v151
	v_pk_add_f32 v[144:145], v[144:145], v[146:147]
	s_nop 0
	v_pk_add_f32 v[6:7], v[6:7], v[144:145]
	s_nop 0
	v_add_f32_e32 v6, v6, v7
	v_mov_b32_e32 v7, v6
	s_nop 1
	v_permlane16_swap_b32 v7, v6
	s_nop 0
	v_add_f32_e32 v6, v7, v6
	v_mov_b32_e32 v7, v6
	s_nop 1
	v_permlane32_swap_b32 v6, v7
	s_nop 0
	v_add_f32_e32 v6, v6, v7
	v_fmamk_f32 v6, v6, 0x3a000000, v221
	v_cmp_gt_f32_e32 vcc, s52, v6
	v_mul_f32_e32 v7, 0x4f800000, v6
	s_nop 0
	v_cndmask_b32_e32 v6, v6, v7, vcc
	v_sqrt_f32_e32 v7, v6
	s_nop 0
	v_add_u32_e32 v144, -1, v7
	v_fma_f32 v145, -v144, v7, v6
	v_cmp_ge_f32_e64 s[6:7], 0, v145
	v_add_u32_e32 v145, 1, v7
	s_nop 0
	v_cndmask_b32_e64 v144, v7, v144, s[6:7]
	v_fma_f32 v7, -v145, v7, v6
	v_cmp_lt_f32_e64 s[6:7], 0, v7
	s_nop 1
	v_cndmask_b32_e64 v7, v144, v145, s[6:7]
	v_mul_f32_e32 v144, 0x37800000, v7
	v_cndmask_b32_e32 v7, v7, v144, vcc
	v_cmp_class_f32_e32 vcc, v6, v226
	s_nop 1
	v_cndmask_b32_e32 v6, v7, v6, vcc
	v_div_scale_f32 v7, s[6:7], v6, v6, 1.0
	v_rcp_f32_e32 v144, v7
	s_nop 0
	v_fma_f32 v145, -v7, v144, 1.0
	v_fmac_f32_e32 v144, v145, v144
	v_div_scale_f32 v145, vcc, 1.0, v6, 1.0
	v_mul_f32_e32 v146, v145, v144
	v_fma_f32 v147, -v7, v146, v145
	v_fmac_f32_e32 v146, v147, v144
	v_fma_f32 v7, -v7, v146, v145
	v_div_fmas_f32 v7, v7, v144, v146
	v_mov_b32_e32 v144, v140
	v_mov_b32_e32 v145, v136
	v_mov_b32_e32 v136, v141
	v_mov_b32_e32 v140, v142
	v_mov_b32_e32 v141, v138
	v_mov_b32_e32 v138, v143
	v_pk_add_f32 v[136:137], v[144:145], v[136:137]
	v_pk_add_f32 v[138:139], v[140:141], v[138:139]
	v_div_fixup_f32 v6, v7, v6, 1.0
	v_pk_add_f32 v[136:137], v[136:137], v[138:139]
	s_nop 0
	v_add_f32_e32 v7, v136, v137
	v_mov_b32_e32 v136, v7
	s_nop 1
	v_permlane16_swap_b32 v7, v136
	s_nop 0
	v_add_f32_e32 v7, v7, v136
	v_mov_b32_e32 v136, v7
	s_nop 1
	v_permlane32_swap_b32 v136, v7
	s_nop 0
	v_add_f32_e32 v7, v136, v7
	v_fmamk_f32 v7, v7, 0x3a000000, v221
	v_cmp_gt_f32_e32 vcc, s52, v7
	v_mul_f32_e32 v136, 0x4f800000, v7
	s_nop 0
	v_cndmask_b32_e32 v7, v7, v136, vcc
	v_sqrt_f32_e32 v136, v7
	s_nop 0
	v_add_u32_e32 v137, -1, v136
	v_fma_f32 v138, -v137, v136, v7
	v_cmp_ge_f32_e64 s[6:7], 0, v138
	v_add_u32_e32 v138, 1, v136
	s_nop 0
	v_cndmask_b32_e64 v137, v136, v137, s[6:7]
	v_fma_f32 v136, -v138, v136, v7
	v_cmp_lt_f32_e64 s[6:7], 0, v136
	s_nop 1
	v_cndmask_b32_e64 v136, v137, v138, s[6:7]
	v_mul_f32_e32 v137, 0x37800000, v136
	v_cndmask_b32_e32 v136, v136, v137, vcc
	v_cmp_class_f32_e32 vcc, v7, v226
	s_nop 1
	v_cndmask_b32_e32 v7, v136, v7, vcc
	v_div_scale_f32 v136, s[6:7], v7, v7, 1.0
	v_rcp_f32_e32 v137, v136
	s_mov_b64 s[6:7], 0
	v_fma_f32 v138, -v136, v137, 1.0
	v_fmac_f32_e32 v137, v138, v137
	v_div_scale_f32 v138, vcc, 1.0, v7, 1.0
	v_mul_f32_e32 v139, v138, v137
	v_fma_f32 v140, -v136, v139, v138
	v_fmac_f32_e32 v139, v140, v137
	v_fma_f32 v136, -v136, v139, v138
	v_div_fmas_f32 v136, v136, v137, v139
	v_div_fixup_f32 v7, v136, v7, 1.0
	v_mov_b64_e32 v[136:137], v[192:193]

; __device__ __forceinline__ unsigned cvt_pk_bf16(float lo, float hi) { unsigned r; asm volatile("v_cvt_pk_bf16_f32 %0, %1, %2" : "=v"(r) : "v"(lo), "v"(hi)); return r; }
; __device__ __forceinline__ float silu_mul(float g, float u) { const float e = __builtin_amdgcn_exp2f(g * -1.4426950408889634f); return g * u * __builtin_amdgcn_rcpf(1.0f + e); }
; #define PG8_BAR __builtin_amdgcn_s_barrier()
;     __device__ __forceinline__ void operator()(const f32x4 (&acc)[2][2][4][2], const Unit& u, int wr, int wc, int fr, int fq, const PG8_LAS float* rc, bool cached) const {
;     ...
;             for (int m = 0; m < 4; ++m) { const int row = row0 + ai * HALF + m * 16; const float rs = rsv[ai * 4 + m];
;                 const f32x4 g0 = acc[ai][0][m][0] * rs, g1 = acc[ai][0][m][1] * rs, u0 = acc[ai][1][m][0] * rs, u1 = acc[ai][1][m][1] * rs;
;                 u32x4 w; w.x = cvt_pk_bf16(silu_mul(g0[0], u0[0]), silu_mul(g0[1], u0[1])); w.y = cvt_pk_bf16(silu_mul(g0[2], u0[2]), silu_mul(g0[3], u0[3]));
;                 w.z = cvt_pk_bf16(silu_mul(g1[0], u1[0]), silu_mul(g1[1], u1[1])); w.w = cvt_pk_bf16(silu_mul(g1[2], u1[2]), silu_mul(g1[3], u1[3]));
;                 *(u32x4*)(H + (size_t)row * 5632 + col0) = w; }
; template <class Epi, class Sched, bool ALIGN_EPI = false, bool SP2 = false, bool HALFM = false, bool AMAP = false>
; __device__ __forceinline__ void gemm_phase(PG8_LAS unsigned char* lds, const Gemm g, const Sched& S, const Epi& E, int tid_in) {
;     ...
;         if constexpr (ALIGN_EPI) { if (wr == 0) PG8_BAR; }
.LBB0_170:
	s_waitcnt lgkmcnt(0)
	v_pk_mul_f32 v[132:133], v[132:133], v[0:1] op_sel_hi:[1,0]
	v_pk_mul_f32 v[124:125], v[124:125], v[0:1] op_sel_hi:[1,0]
	v_mul_f32_e32 v140, 0xbfb8aa3b, v132
	v_exp_f32_e32 v140, v140
	v_mul_f32_e32 v124, v132, v124
	v_mul_f32_e32 v125, v133, v125
	v_pk_mul_f32 v[134:135], v[134:135], v[0:1] op_sel_hi:[1,0]
	v_add_f32_e32 v132, 1.0, v140
	v_rcp_f32_e32 v132, v132
	v_pk_mul_f32 v[126:127], v[126:127], v[0:1] op_sel_hi:[1,0]
	v_pk_mul_f32 v[128:129], v[128:129], v[0:1] op_sel_hi:[1,0]
	v_mul_f32_e32 v126, v134, v126
	v_mul_f32_e32 v124, v124, v132
	v_mul_f32_e32 v132, 0xbfb8aa3b, v133
	v_exp_f32_e32 v132, v132
	v_mul_f32_e32 v127, v135, v127
	v_pk_mul_f32 v[120:121], v[120:121], v[0:1] op_sel_hi:[1,0]
	v_pk_mul_f32 v[130:131], v[130:131], v[0:1] op_sel_hi:[1,0]
	v_add_f32_e32 v132, 1.0, v132
	v_rcp_f32_e32 v132, v132
	v_mul_f32_e32 v120, v128, v120
	v_mul_f32_e32 v121, v129, v121
	v_pk_mul_f32 v[122:123], v[122:123], v[0:1] op_sel_hi:[1,0]
	v_mul_f32_e32 v125, v125, v132
	v_cvt_pk_bf16_f32 v124, v124, v125
	v_mul_f32_e32 v125, 0xbfb8aa3b, v134
	v_exp_f32_e32 v125, v125
	v_lshl_or_b32 v138, s49, 7, v207
	v_add_u32_e32 v138, v138, v209
	v_ashrrev_i32_e32 v139, 31, v138
	v_add_f32_e32 v125, 1.0, v125
	v_rcp_f32_e32 v125, v125
	v_pk_mul_f32 v[116:117], v[116:117], v[0:1] op_sel:[0,1]
	v_pk_mul_f32 v[118:119], v[118:119], v[0:1] op_sel:[0,1]
	v_pk_mul_f32 v[114:115], v[114:115], v[0:1] op_sel:[0,1]
	v_mul_f32_e32 v125, v126, v125
	v_mul_f32_e32 v126, 0xbfb8aa3b, v135
	v_exp_f32_e32 v126, v126
	v_pk_mul_f32 v[112:113], v[112:113], v[0:1] op_sel:[0,1]
	v_pk_mul_f32 v[110:111], v[110:111], v[0:1] op_sel:[0,1]
	v_pk_mul_f32 v[108:109], v[108:109], v[0:1] op_sel:[0,1]
	v_add_f32_e32 v126, 1.0, v126
	v_rcp_f32_e32 v126, v126
	v_pk_mul_f32 v[100:101], v[100:101], v[2:3] op_sel_hi:[1,0]
	v_pk_mul_f32 v[98:99], v[98:99], v[2:3] op_sel_hi:[1,0]
	v_pk_mul_f32 v[96:97], v[96:97], v[2:3] op_sel_hi:[1,0]
	v_mul_f32_e32 v126, v127, v126
	v_cvt_pk_bf16_f32 v125, v125, v126
	v_mul_f32_e32 v126, 0xbfb8aa3b, v128
	v_exp_f32_e32 v126, v126
	v_pk_mul_f32 v[94:95], v[94:95], v[2:3] op_sel_hi:[1,0]
	v_pk_mul_f32 v[92:93], v[92:93], v[2:3] op_sel_hi:[1,0]
	v_pk_mul_f32 v[66:67], v[66:67], v[4:5] op_sel_hi:[1,0]
	v_add_f32_e32 v126, 1.0, v126
	v_rcp_f32_e32 v126, v126
	v_pk_mul_f32 v[64:65], v[64:65], v[4:5] op_sel_hi:[1,0]
	v_pk_mul_f32 v[62:63], v[62:63], v[4:5] op_sel_hi:[1,0]
	v_pk_mul_f32 v[60:61], v[60:61], v[4:5] op_sel_hi:[1,0]
	v_mul_f32_e32 v120, v120, v126
	v_mul_f32_e32 v126, 0xbfb8aa3b, v129
	v_exp_f32_e32 v126, v126
	v_pk_mul_f32 v[58:59], v[58:59], v[4:5] op_sel_hi:[1,0]
	v_pk_mul_f32 v[56:57], v[56:57], v[4:5] op_sel_hi:[1,0]
	v_pk_mul_f32 v[32:33], v[32:33], v[6:7] op_sel_hi:[1,0]
	v_add_f32_e32 v126, 1.0, v126
	v_rcp_f32_e32 v126, v126
	v_pk_mul_f32 v[30:31], v[30:31], v[6:7] op_sel_hi:[1,0]
	v_pk_mul_f32 v[28:29], v[28:29], v[6:7] op_sel_hi:[1,0]
	v_pk_mul_f32 v[26:27], v[26:27], v[6:7] op_sel_hi:[1,0]
	v_mul_f32_e32 v121, v121, v126
	v_cvt_pk_bf16_f32 v126, v120, v121
	v_mul_f32_e32 v120, 0xbfb8aa3b, v130
	v_exp_f32_e32 v120, v120
	v_mul_f32_e32 v121, v130, v122
	v_mul_f32_e32 v122, v131, v123
	v_pk_mul_f32 v[24:25], v[24:25], v[6:7] op_sel_hi:[1,0]
	v_add_f32_e32 v120, 1.0, v120
	v_rcp_f32_e32 v120, v120
	s_andn2_b64 vcc, exec, s[4:5]
	v_mul_f32_e32 v120, v121, v120
	v_mul_f32_e32 v121, 0xbfb8aa3b, v131
	v_exp_f32_e32 v121, v121
	s_nop 0
	v_add_f32_e32 v121, 1.0, v121
	v_rcp_f32_e32 v121, v121
	s_nop 0
	v_mul_f32_e32 v121, v122, v121
	v_cvt_pk_bf16_f32 v127, v120, v121
	v_mov_b64_e32 v[120:121], s[16:17]
	v_mad_u64_u32 v[128:129], s[6:7], v200, s57, v[120:121]
	v_mov_b32_e32 v122, v129
	v_mad_u64_u32 v[122:123], s[6:7], v201, s57, v[122:123]
	v_mov_b32_e32 v129, v122
	v_lshlrev_b64 v[122:123], 1, v[138:139]
	v_lshl_add_u64 v[128:129], v[128:129], 0, v[122:123]
	global_store_dwordx4 v[128:129], v[124:127], off
	s_nop 1
	v_pk_mul_f32 v[124:125], v[106:107], v[0:1] op_sel:[0,1]
	v_pk_mul_f32 v[0:1], v[104:105], v[0:1] op_sel:[0,1]
	v_mul_f32_e32 v104, 0xbfb8aa3b, v116
	v_exp_f32_e32 v104, v104
	v_mul_f32_e32 v105, v116, v108
	v_mul_f32_e32 v106, v117, v109
	v_mul_f32_e32 v107, v119, v111
	v_add_f32_e32 v104, 1.0, v104
	v_rcp_f32_e32 v104, v104
	v_mul_f32_e32 v0, v112, v0
	v_mul_f32_e32 v1, v113, v1
	v_mul_f32_e32 v104, v105, v104
	s_cmp_lg_u64 s[20:21], 0
	s_cbranch_scc0 .Lgu_nb
	s_barrier
; __device__ __forceinline__ unsigned cvt_pk_bf16(float lo, float hi) { unsigned r; asm volatile("v_cvt_pk_bf16_f32 %0, %1, %2" : "=v"(r) : "v"(lo), "v"(hi)); return r; }
; __device__ __forceinline__ float silu_mul(float g, float u) { const float e = __builtin_amdgcn_exp2f(g * -1.4426950408889634f); return g * u * __builtin_amdgcn_rcpf(1.0f + e); }
;     __device__ __forceinline__ void operator()(const f32x4 (&acc)[2][2][4][2], const Unit& u, int wr, int wc, int fr, int fq, const PG8_LAS float* rc, bool cached) const {
;     ...
;             for (int m = 0; m < 4; ++m) { const int row = row0 + ai * HALF + m * 16; const float rs = rsv[ai * 4 + m];
;                 const f32x4 g0 = acc[ai][0][m][0] * rs, g1 = acc[ai][0][m][1] * rs, u0 = acc[ai][1][m][0] * rs, u1 = acc[ai][1][m][1] * rs;
;                 u32x4 w; w.x = cvt_pk_bf16(silu_mul(g0[0], u0[0]), silu_mul(g0[1], u0[1])); w.y = cvt_pk_bf16(silu_mul(g0[2], u0[2]), silu_mul(g0[3], u0[3]));
;                 w.z = cvt_pk_bf16(silu_mul(g1[0], u1[0]), silu_mul(g1[1], u1[1])); w.w = cvt_pk_bf16(silu_mul(g1[2], u1[2]), silu_mul(g1[3], u1[3]));
;                 *(u32x4*)(H + (size_t)row * 5632 + col0) = w; }
.Lgu_nb:
	v_mul_f32_e32 v105, 0xbfb8aa3b, v117
	v_exp_f32_e32 v105, v105
	s_nop 0
	v_add_f32_e32 v105, 1.0, v105
	v_rcp_f32_e32 v105, v105
	s_nop 0
	v_mul_f32_e32 v105, v106, v105
	v_cvt_pk_bf16_f32 v104, v104, v105
	v_mul_f32_e32 v105, 0xbfb8aa3b, v118
	v_exp_f32_e32 v105, v105
	v_mul_f32_e32 v106, v118, v110
	v_add_f32_e32 v105, 1.0, v105
	v_rcp_f32_e32 v105, v105
	s_nop 0
	v_mul_f32_e32 v105, v106, v105
	v_mul_f32_e32 v106, 0xbfb8aa3b, v119
	v_exp_f32_e32 v106, v106
	s_nop 0
	v_add_f32_e32 v106, 1.0, v106
	v_rcp_f32_e32 v106, v106
	s_nop 0
	v_mul_f32_e32 v106, v107, v106
	v_cvt_pk_bf16_f32 v105, v105, v106
	v_mul_f32_e32 v106, 0xbfb8aa3b, v112
	v_exp_f32_e32 v106, v106
	v_mul_f32_e32 v107, v115, v125
	v_add_f32_e32 v106, 1.0, v106
	v_rcp_f32_e32 v106, v106
	s_nop 0
	v_mul_f32_e32 v0, v0, v106
	v_mul_f32_e32 v106, 0xbfb8aa3b, v113
	v_exp_f32_e32 v106, v106
	s_nop 0
	v_add_f32_e32 v106, 1.0, v106
	v_rcp_f32_e32 v106, v106
	s_nop 0
	v_mul_f32_e32 v1, v1, v106
	v_cvt_pk_bf16_f32 v106, v0, v1
	v_mul_f32_e32 v0, 0xbfb8aa3b, v114
	v_exp_f32_e32 v0, v0
	v_mul_f32_e32 v1, v114, v124
	v_add_f32_e32 v0, 1.0, v0
	v_rcp_f32_e32 v0, v0
	s_nop 0
	v_mul_f32_e32 v0, v1, v0
	v_mul_f32_e32 v1, 0xbfb8aa3b, v115
	v_exp_f32_e32 v1, v1
	s_nop 0
	v_add_f32_e32 v1, 1.0, v1
	v_rcp_f32_e32 v1, v1
	s_nop 0
	v_mul_f32_e32 v1, v107, v1
	v_cvt_pk_bf16_f32 v107, v0, v1
	v_mad_u64_u32 v[0:1], s[6:7], v198, s57, v[120:121]
	v_mov_b32_e32 v108, v1
	v_mad_u64_u32 v[108:109], s[6:7], v199, s57, v[108:109]
	v_mov_b32_e32 v1, v108
	v_lshl_add_u64 v[0:1], v[0:1], 0, v[122:123]
	global_store_dwordx4 v[0:1], v[104:107], off
	v_pk_mul_f32 v[0:1], v[102:103], v[2:3] op_sel_hi:[1,0]
	v_pk_mul_f32 v[102:103], v[90:91], v[2:3] op_sel_hi:[1,0]
	v_pk_mul_f32 v[90:91], v[88:89], v[2:3] op_sel_hi:[1,0]
	v_mul_f32_e32 v2, 0xbfb8aa3b, v100
	v_exp_f32_e32 v2, v2
	v_mul_f32_e32 v88, v100, v92
	v_mul_f32_e32 v89, v101, v93
	v_add_f32_e32 v2, 1.0, v2
	v_rcp_f32_e32 v2, v2
	s_nop 0
	v_mul_f32_e32 v2, v88, v2
	v_mul_f32_e32 v88, 0xbfb8aa3b, v101
	v_exp_f32_e32 v88, v88
	s_nop 0
	v_add_f32_e32 v88, 1.0, v88
	v_rcp_f32_e32 v88, v88
	s_nop 0
	v_mul_f32_e32 v88, v89, v88
	v_cvt_pk_bf16_f32 v88, v2, v88
	v_mul_f32_e32 v2, 0xbfb8aa3b, v0
	v_exp_f32_e32 v2, v2
	v_mul_f32_e32 v0, v0, v94
	v_add_f32_e32 v2, 1.0, v2
	v_rcp_f32_e32 v2, v2
	s_nop 0
	v_mul_f32_e32 v0, v0, v2
	v_mul_f32_e32 v2, 0xbfb8aa3b, v1
	v_exp_f32_e32 v2, v2
	v_mul_f32_e32 v1, v1, v95
	v_add_f32_e32 v2, 1.0, v2
	v_rcp_f32_e32 v2, v2
	s_nop 0
	v_mul_f32_e32 v1, v1, v2
	v_cvt_pk_bf16_f32 v89, v0, v1
	v_mul_f32_e32 v0, 0xbfb8aa3b, v96
	v_exp_f32_e32 v0, v0
	v_mul_f32_e32 v1, v96, v90
	v_mul_f32_e32 v2, v97, v91
	v_add_f32_e32 v0, 1.0, v0
	v_rcp_f32_e32 v0, v0
	s_nop 0
	v_mul_f32_e32 v0, v1, v0
	v_mul_f32_e32 v1, 0xbfb8aa3b, v97
	v_exp_f32_e32 v1, v1
	s_nop 0
	v_add_f32_e32 v1, 1.0, v1
	v_rcp_f32_e32 v1, v1
	s_nop 0
	v_mul_f32_e32 v1, v2, v1
	v_cvt_pk_bf16_f32 v90, v0, v1
	v_mul_f32_e32 v0, 0xbfb8aa3b, v98
	v_exp_f32_e32 v0, v0
	v_mul_f32_e32 v1, v98, v102
	v_mul_f32_e32 v2, v99, v103
	v_add_f32_e32 v0, 1.0, v0
	v_rcp_f32_e32 v0, v0
	s_nop 0
	v_mul_f32_e32 v0, v1, v0
	v_mul_f32_e32 v1, 0xbfb8aa3b, v99
	v_exp_f32_e32 v1, v1
	s_nop 0
	v_add_f32_e32 v1, 1.0, v1
	v_rcp_f32_e32 v1, v1
	s_nop 0
	v_mul_f32_e32 v1, v2, v1
	v_cvt_pk_bf16_f32 v91, v0, v1
	v_mad_u64_u32 v[0:1], s[6:7], v196, s57, v[120:121]
	v_mov_b32_e32 v2, v1
	v_mad_u64_u32 v[92:93], s[6:7], v197, s57, v[2:3]
	v_mov_b32_e32 v1, v92
	v_lshl_add_u64 v[0:1], v[0:1], 0, v[122:123]
	global_store_dwordx4 v[0:1], v[88:91], off
	v_mov_b32_e32 v0, v3
	v_pk_mul_f32 v[84:85], v[84:85], v[0:1] op_sel_hi:[1,0]
	v_pk_mul_f32 v[2:3], v[86:87], v[0:1] op_sel_hi:[1,0]
	v_pk_mul_f32 v[82:83], v[82:83], v[0:1] op_sel_hi:[1,0]
	v_pk_mul_f32 v[80:81], v[80:81], v[0:1] op_sel_hi:[1,0]
	v_pk_mul_f32 v[78:79], v[78:79], v[0:1] op_sel_hi:[1,0]
	v_pk_mul_f32 v[76:77], v[76:77], v[0:1] op_sel_hi:[1,0]
	v_pk_mul_f32 v[74:75], v[74:75], v[0:1] op_sel_hi:[1,0]
	v_pk_mul_f32 v[72:73], v[72:73], v[0:1] op_sel_hi:[1,0]
	v_mul_f32_e32 v0, 0xbfb8aa3b, v84
	v_exp_f32_e32 v0, v0
	v_mul_f32_e32 v1, v84, v76
	v_mul_f32_e32 v76, v85, v77
	v_add_f32_e32 v0, 1.0, v0
	v_rcp_f32_e32 v0, v0
	s_nop 0
	v_mul_f32_e32 v0, v1, v0
	v_mul_f32_e32 v1, 0xbfb8aa3b, v85
	v_exp_f32_e32 v1, v1
	s_nop 0
	v_add_f32_e32 v1, 1.0, v1
	v_rcp_f32_e32 v1, v1
	s_nop 0
	v_mul_f32_e32 v1, v76, v1
	v_cvt_pk_bf16_f32 v0, v0, v1
	v_mul_f32_e32 v1, 0xbfb8aa3b, v2
	v_exp_f32_e32 v1, v1
	v_mul_f32_e32 v2, v2, v78
	v_add_f32_e32 v1, 1.0, v1
	v_rcp_f32_e32 v1, v1
	s_nop 0
	v_mul_f32_e32 v1, v2, v1
	v_mul_f32_e32 v2, 0xbfb8aa3b, v3
	v_exp_f32_e32 v2, v2
	v_mul_f32_e32 v3, v3, v79
	v_add_f32_e32 v2, 1.0, v2
	v_rcp_f32_e32 v2, v2
	s_nop 0
	v_mul_f32_e32 v2, v3, v2
	v_cvt_pk_bf16_f32 v1, v1, v2
	v_mul_f32_e32 v2, 0xbfb8aa3b, v80
	v_exp_f32_e32 v2, v2
	v_mul_f32_e32 v3, v80, v72
	v_mul_f32_e32 v72, v81, v73
	v_mul_f32_e32 v73, v83, v75
	v_add_f32_e32 v2, 1.0, v2
	v_rcp_f32_e32 v2, v2
	s_nop 0
	v_mul_f32_e32 v2, v3, v2
	v_mul_f32_e32 v3, 0xbfb8aa3b, v81
	v_exp_f32_e32 v3, v3
	s_nop 0
	v_add_f32_e32 v3, 1.0, v3
	v_rcp_f32_e32 v3, v3
	s_nop 0
	v_mul_f32_e32 v3, v72, v3
	v_cvt_pk_bf16_f32 v2, v2, v3
	v_mul_f32_e32 v3, 0xbfb8aa3b, v82
	v_exp_f32_e32 v3, v3
	v_mul_f32_e32 v72, v82, v74
	v_add_f32_e32 v3, 1.0, v3
	v_rcp_f32_e32 v3, v3
	s_nop 0
	v_mul_f32_e32 v3, v72, v3
	v_mul_f32_e32 v72, 0xbfb8aa3b, v83
	v_exp_f32_e32 v72, v72
	s_nop 0
	v_add_f32_e32 v72, 1.0, v72
	v_rcp_f32_e32 v72, v72
	s_nop 0
	v_mul_f32_e32 v72, v73, v72
	v_cvt_pk_bf16_f32 v3, v3, v72
	v_mad_u64_u32 v[72:73], s[6:7], v194, s57, v[120:121]
	v_mov_b32_e32 v74, v73
	v_mad_u64_u32 v[74:75], s[6:7], v195, s57, v[74:75]
; __device__ __forceinline__ unsigned cvt_pk_bf16(float lo, float hi) { unsigned r; asm volatile("v_cvt_pk_bf16_f32 %0, %1, %2" : "=v"(r) : "v"(lo), "v"(hi)); return r; }
; __device__ __forceinline__ float silu_mul(float g, float u) { const float e = __builtin_amdgcn_exp2f(g * -1.4426950408889634f); return g * u * __builtin_amdgcn_rcpf(1.0f + e); }
;     __device__ __forceinline__ void operator()(const f32x4 (&acc)[2][2][4][2], const Unit& u, int wr, int wc, int fr, int fq, const PG8_LAS float* rc, bool cached) const {
;     ...
;             for (int m = 0; m < 4; ++m) { const int row = row0 + ai * HALF + m * 16; const float rs = rsv[ai * 4 + m];
;                 const f32x4 g0 = acc[ai][0][m][0] * rs, g1 = acc[ai][0][m][1] * rs, u0 = acc[ai][1][m][0] * rs, u1 = acc[ai][1][m][1] * rs;
;                 u32x4 w; w.x = cvt_pk_bf16(silu_mul(g0[0], u0[0]), silu_mul(g0[1], u0[1])); w.y = cvt_pk_bf16(silu_mul(g0[2], u0[2]), silu_mul(g0[3], u0[3]));
;                 w.z = cvt_pk_bf16(silu_mul(g1[0], u1[0]), silu_mul(g1[1], u1[1])); w.w = cvt_pk_bf16(silu_mul(g1[2], u1[2]), silu_mul(g1[3], u1[3]));
;                 *(u32x4*)(H + (size_t)row * 5632 + col0) = w; }
	v_mov_b32_e32 v73, v74
	v_lshl_add_u64 v[72:73], v[72:73], 0, v[122:123]
	global_store_dwordx4 v[72:73], v[0:3], off
	s_nop 1
	v_pk_mul_f32 v[0:1], v[68:69], v[4:5] op_sel_hi:[1,0]
	v_pk_mul_f32 v[2:3], v[70:71], v[4:5] op_sel_hi:[1,0]
	v_mul_f32_e32 v4, 0xbfb8aa3b, v0
	v_exp_f32_e32 v4, v4
	v_mul_f32_e32 v0, v0, v60
	v_add_f32_e32 v4, 1.0, v4
	v_rcp_f32_e32 v4, v4
	s_nop 0
	v_mul_f32_e32 v0, v0, v4
	v_mul_f32_e32 v4, 0xbfb8aa3b, v1
	v_exp_f32_e32 v4, v4
	v_mul_f32_e32 v1, v1, v61
	v_add_f32_e32 v4, 1.0, v4
	v_rcp_f32_e32 v4, v4
	s_nop 0
	v_mul_f32_e32 v1, v1, v4
	v_cvt_pk_bf16_f32 v0, v0, v1
	v_mul_f32_e32 v1, 0xbfb8aa3b, v2
	v_exp_f32_e32 v1, v1
	v_mul_f32_e32 v2, v2, v62
	v_mul_f32_e32 v4, v65, v57
	v_add_f32_e32 v1, 1.0, v1
	v_rcp_f32_e32 v1, v1
	s_nop 0
	v_mul_f32_e32 v1, v2, v1
	v_mul_f32_e32 v2, 0xbfb8aa3b, v3
	v_exp_f32_e32 v2, v2
	v_mul_f32_e32 v3, v3, v63
	v_add_f32_e32 v2, 1.0, v2
	v_rcp_f32_e32 v2, v2
	s_nop 0
	v_mul_f32_e32 v2, v3, v2
	v_cvt_pk_bf16_f32 v1, v1, v2
	v_mul_f32_e32 v2, 0xbfb8aa3b, v64
	v_exp_f32_e32 v2, v2
	v_mul_f32_e32 v3, v64, v56
	v_mul_f32_e32 v56, v67, v59
	v_add_f32_e32 v2, 1.0, v2
	v_rcp_f32_e32 v2, v2
	s_nop 0
	v_mul_f32_e32 v2, v3, v2
	v_mul_f32_e32 v3, 0xbfb8aa3b, v65
	v_exp_f32_e32 v3, v3
	s_nop 0
	v_add_f32_e32 v3, 1.0, v3
	v_rcp_f32_e32 v3, v3
	s_nop 0
	v_mul_f32_e32 v3, v4, v3
	v_cvt_pk_bf16_f32 v2, v2, v3
	v_mul_f32_e32 v3, 0xbfb8aa3b, v66
	v_exp_f32_e32 v3, v3
	v_mul_f32_e32 v4, v66, v58
	v_add_f32_e32 v3, 1.0, v3
	v_rcp_f32_e32 v3, v3
	s_nop 0
	v_mul_f32_e32 v3, v4, v3
	v_mul_f32_e32 v4, 0xbfb8aa3b, v67
	v_exp_f32_e32 v4, v4
	s_nop 0
	v_add_f32_e32 v4, 1.0, v4
	v_rcp_f32_e32 v4, v4
	s_nop 0
	v_mul_f32_e32 v4, v56, v4
	v_mad_u64_u32 v[56:57], s[6:7], v136, s57, v[120:121]
	v_cvt_pk_bf16_f32 v3, v3, v4
	v_mov_b32_e32 v4, v57
	v_mad_u64_u32 v[58:59], s[6:7], v137, s57, v[4:5]
	v_mov_b32_e32 v57, v58
	v_lshl_add_u64 v[56:57], v[56:57], 0, v[122:123]
	global_store_dwordx4 v[56:57], v[0:3], off
	v_add_u32_e32 v56, 16, v192
	s_nop 0
	v_mov_b32_e32 v0, v5
	v_pk_mul_f32 v[4:5], v[52:53], v[0:1] op_sel_hi:[1,0]
	v_pk_mul_f32 v[2:3], v[54:55], v[0:1] op_sel_hi:[1,0]
	v_pk_mul_f32 v[50:51], v[50:51], v[0:1] op_sel_hi:[1,0]
	v_pk_mul_f32 v[48:49], v[48:49], v[0:1] op_sel_hi:[1,0]
	v_pk_mul_f32 v[46:47], v[46:47], v[0:1] op_sel_hi:[1,0]
	v_pk_mul_f32 v[44:45], v[44:45], v[0:1] op_sel_hi:[1,0]
	v_pk_mul_f32 v[42:43], v[42:43], v[0:1] op_sel_hi:[1,0]
	v_pk_mul_f32 v[40:41], v[40:41], v[0:1] op_sel_hi:[1,0]
	v_mul_f32_e32 v0, 0xbfb8aa3b, v4
	v_exp_f32_e32 v0, v0
	v_mul_f32_e32 v1, v4, v44
	v_mul_f32_e32 v4, v5, v45
	v_add_f32_e32 v0, 1.0, v0
	v_rcp_f32_e32 v0, v0
	s_nop 0
	v_mul_f32_e32 v0, v1, v0
	v_mul_f32_e32 v1, 0xbfb8aa3b, v5
	v_exp_f32_e32 v1, v1
	v_mul_f32_e32 v5, v51, v43
	v_add_f32_e32 v1, 1.0, v1
	v_rcp_f32_e32 v1, v1
	s_nop 0
	v_mul_f32_e32 v1, v4, v1
	v_cvt_pk_bf16_f32 v0, v0, v1
	v_mul_f32_e32 v1, 0xbfb8aa3b, v2
	v_exp_f32_e32 v1, v1
	v_mul_f32_e32 v2, v2, v46
	v_mul_f32_e32 v4, v49, v41
	v_add_f32_e32 v1, 1.0, v1
	v_rcp_f32_e32 v1, v1
	s_nop 0
	v_mul_f32_e32 v1, v2, v1
	v_mul_f32_e32 v2, 0xbfb8aa3b, v3
	v_exp_f32_e32 v2, v2
	v_mul_f32_e32 v3, v3, v47
	v_add_f32_e32 v2, 1.0, v2
	v_rcp_f32_e32 v2, v2
	s_nop 0
	v_mul_f32_e32 v2, v3, v2
	v_cvt_pk_bf16_f32 v1, v1, v2
	v_mul_f32_e32 v2, 0xbfb8aa3b, v48
	v_exp_f32_e32 v2, v2
	v_mul_f32_e32 v3, v48, v40
	v_add_u32_e32 v40, 32, v192
	v_add_f32_e32 v2, 1.0, v2
	v_rcp_f32_e32 v2, v2
	s_nop 0
	v_mul_f32_e32 v2, v3, v2
	v_mul_f32_e32 v3, 0xbfb8aa3b, v49
	v_exp_f32_e32 v3, v3
	s_nop 0
	v_add_f32_e32 v3, 1.0, v3
	v_rcp_f32_e32 v3, v3
	s_nop 0
	v_mul_f32_e32 v3, v4, v3
	v_cvt_pk_bf16_f32 v2, v2, v3
	v_mul_f32_e32 v3, 0xbfb8aa3b, v50
	v_exp_f32_e32 v3, v3
	v_mul_f32_e32 v4, v50, v42
	v_add_f32_e32 v3, 1.0, v3
	v_rcp_f32_e32 v3, v3
	s_nop 0
	v_mul_f32_e32 v3, v4, v3
	v_mul_f32_e32 v4, 0xbfb8aa3b, v51
	v_exp_f32_e32 v4, v4
	s_nop 0
	v_add_f32_e32 v4, 1.0, v4
	v_rcp_f32_e32 v4, v4
	s_nop 0
	v_mul_f32_e32 v4, v5, v4
	v_cvt_pk_bf16_f32 v3, v3, v4
	v_mad_i64_i32 v[4:5], s[6:7], v56, s57, v[120:121]
	v_lshl_add_u64 v[4:5], v[4:5], 0, v[122:123]
; #define PG8_LAS __attribute__((address_space(3)))
; __device__ __forceinline__ unsigned cvt_pk_bf16(float lo, float hi) { unsigned r; asm volatile("v_cvt_pk_bf16_f32 %0, %1, %2" : "=v"(r) : "v"(lo), "v"(hi)); return r; }
; __device__ __forceinline__ float silu_mul(float g, float u) { const float e = __builtin_amdgcn_exp2f(g * -1.4426950408889634f); return g * u * __builtin_amdgcn_rcpf(1.0f + e); }
; #define PG8_BAR __builtin_amdgcn_s_barrier()
;     __device__ __forceinline__ void operator()(const f32x4 (&acc)[2][2][4][2], const Unit& u, int wr, int wc, int fr, int fq, const PG8_LAS float* rc, bool cached) const {
;     ...
;             for (int m = 0; m < 4; ++m) { const int row = row0 + ai * HALF + m * 16; const float rs = rsv[ai * 4 + m];
;                 const f32x4 g0 = acc[ai][0][m][0] * rs, g1 = acc[ai][0][m][1] * rs, u0 = acc[ai][1][m][0] * rs, u1 = acc[ai][1][m][1] * rs;
;                 u32x4 w; w.x = cvt_pk_bf16(silu_mul(g0[0], u0[0]), silu_mul(g0[1], u0[1])); w.y = cvt_pk_bf16(silu_mul(g0[2], u0[2]), silu_mul(g0[3], u0[3]));
;                 w.z = cvt_pk_bf16(silu_mul(g1[0], u1[0]), silu_mul(g1[1], u1[1])); w.w = cvt_pk_bf16(silu_mul(g1[2], u1[2]), silu_mul(g1[3], u1[3]));
;                 *(u32x4*)(H + (size_t)row * 5632 + col0) = w; }
; template <class Epi, class Sched, bool ALIGN_EPI = false, bool SP2 = false, bool HALFM = false, bool AMAP = false>
; __device__ __forceinline__ void gemm_phase(PG8_LAS unsigned char* lds, const Gemm g, const Sched& S, const Epi& E, int tid_in) {
;     ...
;         if constexpr (!Epi::AFTER_DRAIN) { if constexpr (Epi::RSTD) E(acc, cur, wr, wc, fr, fq, (const PG8_LAS float*)(lds + STAGE_BYTES), cur.pm == pm0); else E(acc, cur, wr, wc, fr, fq); S.done(cur); }
;         if (!has_next) break;
; #pragma unroll
;         for (int a = 0; a < 2; ++a)
; #pragma unroll
;             for (int b = 0; b < 2; ++b)
; #pragma unroll
;                 for (int m = 0; m < 4; ++m)
; #pragma unroll
;                     for (int n = 0; n < 2; ++n) acc[a][b][m][n] = (f32x4){0.f, 0.f, 0.f, 0.f};
;         cur = nxt; cA = nA; cB = nB; ++ui;
;         if constexpr (ALIGN_EPI) { if (wr == 1) PG8_BAR; }
	global_store_dwordx4 v[4:5], v[0:3], off
	v_pk_mul_f32 v[4:5], v[34:35], v[6:7] op_sel_hi:[1,0]
	s_nop 0
	v_pk_mul_f32 v[0:1], v[36:37], v[6:7] op_sel_hi:[1,0]
	v_pk_mul_f32 v[2:3], v[38:39], v[6:7] op_sel_hi:[1,0]
	v_mul_f32_e32 v6, 0xbfb8aa3b, v0
	v_exp_f32_e32 v6, v6
	v_mul_f32_e32 v0, v0, v28
	v_add_f32_e32 v6, 1.0, v6
	v_rcp_f32_e32 v6, v6
	s_nop 0
	v_mul_f32_e32 v0, v0, v6
	v_mul_f32_e32 v6, 0xbfb8aa3b, v1
	v_exp_f32_e32 v6, v6
	v_mul_f32_e32 v1, v1, v29
	v_add_f32_e32 v6, 1.0, v6
	v_rcp_f32_e32 v6, v6
	s_nop 0
	v_mul_f32_e32 v1, v1, v6
	v_cvt_pk_bf16_f32 v0, v0, v1
	v_mul_f32_e32 v1, 0xbfb8aa3b, v2
	v_exp_f32_e32 v1, v1
	v_mul_f32_e32 v2, v2, v30
	v_mul_f32_e32 v6, v33, v25
	v_add_f32_e32 v1, 1.0, v1
	v_rcp_f32_e32 v1, v1
	s_nop 0
	v_mul_f32_e32 v1, v2, v1
	v_mul_f32_e32 v2, 0xbfb8aa3b, v3
	v_exp_f32_e32 v2, v2
	v_mul_f32_e32 v3, v3, v31
	v_add_f32_e32 v2, 1.0, v2
	v_rcp_f32_e32 v2, v2
	s_nop 0
	v_mul_f32_e32 v2, v3, v2
	v_cvt_pk_bf16_f32 v1, v1, v2
	v_mul_f32_e32 v2, 0xbfb8aa3b, v32
	v_exp_f32_e32 v2, v2
	v_mul_f32_e32 v3, v32, v24
	v_add_u32_e32 v24, 48, v192
	v_add_f32_e32 v2, 1.0, v2
	v_rcp_f32_e32 v2, v2
	s_nop 0
	v_mul_f32_e32 v2, v3, v2
	v_mul_f32_e32 v3, 0xbfb8aa3b, v33
	v_exp_f32_e32 v3, v3
	s_nop 0
	v_add_f32_e32 v3, 1.0, v3
	v_rcp_f32_e32 v3, v3
	s_nop 0
	v_mul_f32_e32 v3, v6, v3
	v_cvt_pk_bf16_f32 v2, v2, v3
	v_mul_f32_e32 v3, 0xbfb8aa3b, v4
	v_exp_f32_e32 v3, v3
	v_mul_f32_e32 v4, v4, v26
	v_add_f32_e32 v3, 1.0, v3
	v_rcp_f32_e32 v3, v3
	s_nop 0
	v_mul_f32_e32 v3, v4, v3
	v_mul_f32_e32 v4, 0xbfb8aa3b, v5
	v_exp_f32_e32 v4, v4
	v_mul_f32_e32 v5, v5, v27
	v_add_f32_e32 v4, 1.0, v4
	v_rcp_f32_e32 v4, v4
	s_nop 0
	v_mul_f32_e32 v4, v5, v4
	v_cvt_pk_bf16_f32 v3, v3, v4
	v_mad_i64_i32 v[4:5], s[6:7], v40, s57, v[120:121]
	v_lshl_add_u64 v[4:5], v[4:5], 0, v[122:123]
	global_store_dwordx4 v[4:5], v[0:3], off
	s_nop 1
	v_mov_b32_e32 v0, v7
	v_pk_mul_f32 v[4:5], v[20:21], v[0:1] op_sel_hi:[1,0]
	v_pk_mul_f32 v[2:3], v[22:23], v[0:1] op_sel_hi:[1,0]
	v_pk_mul_f32 v[6:7], v[18:19], v[0:1] op_sel_hi:[1,0]
	v_pk_mul_f32 v[16:17], v[16:17], v[0:1] op_sel_hi:[1,0]
	v_pk_mul_f32 v[14:15], v[14:15], v[0:1] op_sel_hi:[1,0]
	v_pk_mul_f32 v[12:13], v[12:13], v[0:1] op_sel_hi:[1,0]
	v_pk_mul_f32 v[10:11], v[10:11], v[0:1] op_sel_hi:[1,0]
	v_pk_mul_f32 v[8:9], v[8:9], v[0:1] op_sel_hi:[1,0]
	v_mul_f32_e32 v0, 0xbfb8aa3b, v4
	v_exp_f32_e32 v0, v0
	v_mul_f32_e32 v1, v4, v12
	v_mul_f32_e32 v4, v5, v13
	v_add_f32_e32 v0, 1.0, v0
	v_rcp_f32_e32 v0, v0
	s_nop 0
	v_mul_f32_e32 v0, v1, v0
	v_mul_f32_e32 v1, 0xbfb8aa3b, v5
	v_exp_f32_e32 v1, v1
	v_mul_f32_e32 v5, v7, v11
	v_add_f32_e32 v1, 1.0, v1
	v_rcp_f32_e32 v1, v1
	s_nop 0
	v_mul_f32_e32 v1, v4, v1
	v_cvt_pk_bf16_f32 v0, v0, v1
	v_mul_f32_e32 v1, 0xbfb8aa3b, v2
	v_exp_f32_e32 v1, v1
	v_mul_f32_e32 v2, v2, v14
	v_mul_f32_e32 v4, v17, v9
	v_add_f32_e32 v1, 1.0, v1
	v_rcp_f32_e32 v1, v1
	s_nop 0
	v_mul_f32_e32 v1, v2, v1
	v_mul_f32_e32 v2, 0xbfb8aa3b, v3
	v_exp_f32_e32 v2, v2
	v_mul_f32_e32 v3, v3, v15
	v_add_f32_e32 v2, 1.0, v2
	v_rcp_f32_e32 v2, v2
	s_nop 0
	v_mul_f32_e32 v2, v3, v2
	v_cvt_pk_bf16_f32 v1, v1, v2
	v_mul_f32_e32 v2, 0xbfb8aa3b, v16
	v_exp_f32_e32 v2, v2
	v_mul_f32_e32 v3, v16, v8
	v_add_f32_e32 v2, 1.0, v2
	v_rcp_f32_e32 v2, v2
	s_nop 0
	v_mul_f32_e32 v2, v3, v2
	v_mul_f32_e32 v3, 0xbfb8aa3b, v17
	v_exp_f32_e32 v3, v3
	s_nop 0
	v_add_f32_e32 v3, 1.0, v3
	v_rcp_f32_e32 v3, v3
	s_nop 0
	v_mul_f32_e32 v3, v4, v3
	v_cvt_pk_bf16_f32 v2, v2, v3
	v_mul_f32_e32 v3, 0xbfb8aa3b, v6
	v_exp_f32_e32 v3, v3
	v_mul_f32_e32 v4, v6, v10
	v_add_f32_e32 v3, 1.0, v3
	v_rcp_f32_e32 v3, v3
	s_nop 0
	v_mul_f32_e32 v3, v4, v3
	v_mul_f32_e32 v4, 0xbfb8aa3b, v7
	v_exp_f32_e32 v4, v4
	s_nop 0
	v_add_f32_e32 v4, 1.0, v4
	v_rcp_f32_e32 v4, v4
	s_nop 0
	v_mul_f32_e32 v4, v5, v4
	v_cvt_pk_bf16_f32 v3, v3, v4
	v_mad_i64_i32 v[4:5], s[6:7], v24, s57, v[120:121]
	v_lshl_add_u64 v[4:5], v[4:5], 0, v[122:123]
	s_mov_b64 s[6:7], -1
	global_store_dwordx4 v[4:5], v[0:3], off
	s_cbranch_vccnz .LBB0_159
	s_andn2_b64 vcc, exec, s[14:15]
	s_cbranch_vccnz .LBB0_158
	s_barrier
	s_branch .LBB0_158
